# FFN up-projection GEMMs: the next unit's SA(1,1) stage is issued by the last K iteration (before the epilogue stores in vmcnt order); the peeled first iteration of later units skips it and waits vmcnt
# speedup vs baseline: 1.0064x; 1.0061x over previous
; #define PG8_STAGE(bufoff, gbase, voff) do { _Pragma("unroll") for (int _i = 0; _i < 2; ++_i) \
;         __builtin_amdgcn_global_load_lds((const unsigned*)((const char*)(gbase) + (voff)[_i]), (LAS unsigned*)(lds + (bufoff) + ldsw + _i * 8192), 16, 0, 0); } while (0)
; #define PG8_LDA(dst, b, h) do { _Pragma("unroll") for (int m = 0; m < 4; ++m) _Pragma("unroll") for (int k = 0; k < 2; ++k) dst[m][k] = *(const LAS bf16x8*)(lds + PG8_SA(b, h) + aoff + m * 2048 + k * 1024); } while (0)
; #define PG8_LDB(dst, b, h) do { _Pragma("unroll") for (int n = 0; n < 2; ++n) _Pragma("unroll") for (int k = 0; k < 2; ++k) dst[n][k] = *(const LAS bf16x8*)(lds + PG8_SB(b, h) + boff + n * 2048 + k * 1024); } while (0)
; #define PG8_WAIT_L(n) asm volatile("s_waitcnt lgkmcnt(" #n ")" ::: "memory")
; #define PG8_BAR __builtin_amdgcn_s_barrier()
; #define PG8_SCHED __builtin_amdgcn_sched_barrier(0)
; template <class Epi, class Sched>
; __device__ __forceinline__ void gemm_phase(LAS unsigned char* lds, const Gemm g, const Sched& S, const Epi& E) {
;     ...
;         const bool has_next = S.next(ui + 1, nxt);
;         const char* nA = has_next ? (const char*)g.A + (size_t)nxt.pm * tstep : cA; const char* nB = has_next ? (const char*)g.Bt + (size_t)nxt.pn * tstep : cB;
;         for (int t = 0; t < nt; t += 2) {
;             const bool last = (t == nt - 2);
;             const char* a1 = cA + (size_t)(t + 1) * kstep;
;             const char* a2 = last ? nA : cA + (size_t)(t + 2) * kstep; const char* b2 = last ? nB : cB + (size_t)(t + 2) * kstep;
;             const char* a3 = a2 + kstep; const char* b3 = b2 + kstep;
;             if (last && has_next) S.a_ready(nxt);
;             PG8_LDB(B0, 0, 0); PG8_SCHED; PG8_LDA(At, 0, 0); PG8_STAGE(PG8_SA(1, 1), a1 + hstep, voffA);
;             PG8_WAIT_L(8); PG8_BAR; PG8_WAIT_L(0); PG8_MMA(0, 0, At, B0); PG8_BAR; PG8_SCHED;
;             PG8_LDB(B1, 0, 1); PG8_STAGE(PG8_SB(0, 0), b2, voffB);
;             PG8_BAR; PG8_WAIT_L(0); PG8_MMA(0, 1, At, B1); PG8_BAR;
;             PG8_LDA(At, 0, 1); PG8_STAGE(PG8_SA(0, 0), a2, voffA);
;             PG8_BAR; PG8_WAIT_L(0); PG8_MMA(1, 0, At, B0); PG8_BAR; PG8_SCHED;
;             PG8_STAGE(PG8_SB(0, 1), b2 + hstep, voffB);
.LBB0_242:
	s_ashr_i32 s15, s14, 31
	v_cmp_lt_i64_e32 vcc, s[16:17], v[142:143]
	s_lshl_b64 s[16:17], s[14:15], 20
	s_add_u32 s16, s29, s16
	s_addc_u32 s17, s30, s17
	s_and_b64 s[18:19], vcc, exec
	s_cselect_b32 s15, s17, s23
	s_cselect_b32 s47, s16, s22
	s_ashr_i32 s9, s8, 31
	s_lshl_b64 s[18:19], s[8:9], 20
	s_add_u32 s18, s50, s18
	s_addc_u32 s19, s51, s19
	s_and_b64 s[26:27], vcc, exec
	s_cselect_b32 s9, s19, s25
	s_cselect_b32 s48, s18, s24
	s_add_u32 s22, s22, 0x80080
	s_addc_u32 s23, s23, 0
	s_add_u32 s49, s24, 0x100
	s_addc_u32 s50, s25, 0
	s_mov_b32 s51, -2
	ds_read_b128 v[152:155], v148
	ds_read_b128 v[156:159], v148 offset:1024
	ds_read_b128 v[160:163], v148 offset:2048
	ds_read_b128 v[164:167], v148 offset:3072
	s_add_u32 s24, s22, 0xfff80080
	s_addc_u32 s25, s23, -1
	s_cmp_eq_u32 s51, 28
	s_cselect_b32 s27, s15, s25
	s_cselect_b32 s26, s47, s24
	s_cselect_b32 s25, s9, s50
	s_cselect_b32 s24, s48, s49
	v_lshl_add_u64 v[200:201], s[22:23], 0, v[138:139]
	s_add_i32 m0, s21, 0xc000
	ds_read_b128 v[168:171], v149
	ds_read_b128 v[172:175], v149 offset:1024
	ds_read_b128 v[176:179], v149 offset:2048
	ds_read_b128 v[180:183], v149 offset:3072
	ds_read_b128 v[184:187], v149 offset:4096
	ds_read_b128 v[188:191], v149 offset:5120
	ds_read_b128 v[192:195], v149 offset:6144
	ds_read_b128 v[196:199], v149 offset:7168
	s_cmp_eq_u32 s38, 1
	s_cbranch_scc0 .Lps_p1_skip
	global_load_lds_dwordx4 v[200:201], off
	v_lshl_add_u64 v[200:201], s[22:23], 0, v[140:141]
	s_add_i32 m0, s21, 0xe000
	s_nop 0
	global_load_lds_dwordx4 v[200:201], off
.Lps_p1_skip:
	s_waitcnt lgkmcnt(8)
	s_barrier
	s_waitcnt lgkmcnt(0)
	s_setprio 1
	s_waitcnt lgkmcnt(0)
	v_mfma_f32_16x16x32_bf16 v[126:129], v[152:155], v[168:171], 0
	v_mfma_f32_16x16x32_bf16 v[118:121], v[160:163], v[168:171], 0
	v_mfma_f32_16x16x32_bf16 v[110:113], v[152:155], v[176:179], 0
	v_mfma_f32_16x16x32_bf16 v[102:105], v[160:163], v[176:179], 0
	v_mfma_f32_16x16x32_bf16 v[94:97], v[152:155], v[184:187], 0
	v_mfma_f32_16x16x32_bf16 v[86:89], v[160:163], v[184:187], 0
	v_mfma_f32_16x16x32_bf16 v[78:81], v[152:155], v[192:195], 0
	v_mfma_f32_16x16x32_bf16 v[70:73], v[160:163], v[192:195], 0
	v_mfma_f32_16x16x32_bf16 v[126:129], v[156:159], v[172:175], v[126:129]
	v_mfma_f32_16x16x32_bf16 v[118:121], v[164:167], v[172:175], v[118:121]
	v_mfma_f32_16x16x32_bf16 v[110:113], v[156:159], v[180:183], v[110:113]
	v_mfma_f32_16x16x32_bf16 v[102:105], v[164:167], v[180:183], v[102:105]
	v_mfma_f32_16x16x32_bf16 v[94:97], v[156:159], v[188:191], v[94:97]
	v_mfma_f32_16x16x32_bf16 v[86:89], v[164:167], v[188:191], v[86:89]
	v_mfma_f32_16x16x32_bf16 v[78:81], v[156:159], v[196:199], v[78:81]
	v_mfma_f32_16x16x32_bf16 v[70:73], v[164:167], v[196:199], v[70:73]
	s_setprio 0
	s_barrier
	s_add_i32 s52, s43, s31
	v_lshl_add_u64 v[204:205], s[24:25], 0, v[132:133]
	s_mov_b32 m0, s52
	ds_read_b128 v[200:203], v150
	ds_read_b128 v[208:211], v150 offset:1024
	ds_read_b128 v[212:215], v150 offset:2048
	ds_read_b128 v[216:219], v150 offset:3072
	global_load_lds_dwordx4 v[204:205], off
	v_lshl_add_u64 v[220:221], s[24:25], 0, v[136:137]
	s_add_i32 m0, s52, 0x2000
	s_nop 0
	global_load_lds_dwordx4 v[220:221], off
	s_barrier
	s_waitcnt lgkmcnt(0)
	s_setprio 1
	s_waitcnt lgkmcnt(0)
	v_mfma_f32_16x16x32_bf16 v[122:125], v[200:203], v[168:171], 0
	v_mfma_f32_16x16x32_bf16 v[114:117], v[212:215], v[168:171], 0
	v_mfma_f32_16x16x32_bf16 v[106:109], v[200:203], v[176:179], 0
	v_mfma_f32_16x16x32_bf16 v[98:101], v[212:215], v[176:179], 0
	v_mfma_f32_16x16x32_bf16 v[90:93], v[200:203], v[184:187], 0
	v_mfma_f32_16x16x32_bf16 v[82:85], v[212:215], v[184:187], 0
	v_mfma_f32_16x16x32_bf16 v[74:77], v[200:203], v[192:195], 0
	v_mfma_f32_16x16x32_bf16 v[66:69], v[212:215], v[192:195], 0
	v_mfma_f32_16x16x32_bf16 v[122:125], v[208:211], v[172:175], v[122:125]
	v_mfma_f32_16x16x32_bf16 v[114:117], v[216:219], v[172:175], v[114:117]
	v_mfma_f32_16x16x32_bf16 v[106:109], v[208:211], v[180:183], v[106:109]
	v_mfma_f32_16x16x32_bf16 v[98:101], v[216:219], v[180:183], v[98:101]
	v_mfma_f32_16x16x32_bf16 v[90:93], v[208:211], v[188:191], v[90:93]
	v_mfma_f32_16x16x32_bf16 v[82:85], v[216:219], v[188:191], v[82:85]
	v_mfma_f32_16x16x32_bf16 v[74:77], v[208:211], v[196:199], v[74:77]
	v_mfma_f32_16x16x32_bf16 v[66:69], v[216:219], v[196:199], v[66:69]
	s_setprio 0
	s_mov_b32 m0, s21
	v_lshl_add_u64 v[222:223], s[26:27], 0, v[130:131]
	s_barrier
	ds_read_b128 v[168:171], v149 offset:16384
	ds_read_b128 v[172:175], v149 offset:17408
	ds_read_b128 v[176:179], v149 offset:18432
	ds_read_b128 v[180:183], v149 offset:19456
	ds_read_b128 v[184:187], v149 offset:20480
	ds_read_b128 v[188:191], v149 offset:21504
	ds_read_b128 v[192:195], v149 offset:22528
	ds_read_b128 v[196:199], v149 offset:23552
	global_load_lds_dwordx4 v[222:223], off
	v_lshl_add_u64 v[224:225], s[26:27], 0, v[134:135]
	s_mov_b32 m0, s35
	s_nop 0
	global_load_lds_dwordx4 v[224:225], off
	s_barrier
	s_waitcnt lgkmcnt(0)
	s_setprio 1
	s_waitcnt lgkmcnt(0)
	v_mfma_f32_16x16x32_bf16 v[62:65], v[152:155], v[168:171], 0
	v_mfma_f32_16x16x32_bf16 v[54:57], v[160:163], v[168:171], 0
	v_mfma_f32_16x16x32_bf16 v[46:49], v[152:155], v[176:179], 0
	v_mfma_f32_16x16x32_bf16 v[38:41], v[160:163], v[176:179], 0
	v_mfma_f32_16x16x32_bf16 v[30:33], v[152:155], v[184:187], 0
	v_mfma_f32_16x16x32_bf16 v[22:25], v[160:163], v[184:187], 0
	v_mfma_f32_16x16x32_bf16 v[14:17], v[152:155], v[192:195], 0
	v_mfma_f32_16x16x32_bf16 v[6:9], v[160:163], v[192:195], 0
	v_mfma_f32_16x16x32_bf16 v[62:65], v[156:159], v[172:175], v[62:65]
	v_mfma_f32_16x16x32_bf16 v[54:57], v[164:167], v[172:175], v[54:57]
	v_mfma_f32_16x16x32_bf16 v[46:49], v[156:159], v[180:183], v[46:49]
	v_mfma_f32_16x16x32_bf16 v[38:41], v[164:167], v[180:183], v[38:41]
	v_mfma_f32_16x16x32_bf16 v[30:33], v[156:159], v[188:191], v[30:33]
	v_mfma_f32_16x16x32_bf16 v[22:25], v[164:167], v[188:191], v[22:25]
	v_mfma_f32_16x16x32_bf16 v[14:17], v[156:159], v[196:199], v[14:17]
	v_mfma_f32_16x16x32_bf16 v[6:9], v[164:167], v[196:199], v[6:9]
	s_setprio 0
	s_barrier
	s_add_u32 s52, s24, 0x80000
	s_addc_u32 s53, s25, 0
	s_add_i32 s54, s44, s31
	v_lshl_add_u64 v[152:153], s[52:53], 0, v[132:133]
	s_mov_b32 m0, s54
	s_nop 0
	global_load_lds_dwordx4 v[152:153], off
	v_lshl_add_u64 v[152:153], s[52:53], 0, v[136:137]
	s_add_i32 m0, s54, 0x2000
	s_nop 0
	global_load_lds_dwordx4 v[152:153], off
	s_cmp_eq_u32 s38, 1
	s_cbranch_scc1 .Lpw_p1_strict
	s_waitcnt vmcnt(14)
	s_branch .Lpw_p1_go

; #define PG8_STAGE(bufoff, gbase, voff) do { _Pragma("unroll") for (int _i = 0; _i < 2; ++_i) \
;         __builtin_amdgcn_global_load_lds((const unsigned*)((const char*)(gbase) + (voff)[_i]), (LAS unsigned*)(lds + (bufoff) + ldsw + _i * 8192), 16, 0, 0); } while (0)
; #define PG8_LDA(dst, b, h) do { _Pragma("unroll") for (int m = 0; m < 4; ++m) _Pragma("unroll") for (int k = 0; k < 2; ++k) dst[m][k] = *(const LAS bf16x8*)(lds + PG8_SA(b, h) + aoff + m * 2048 + k * 1024); } while (0)
; #define PG8_LDB(dst, b, h) do { _Pragma("unroll") for (int n = 0; n < 2; ++n) _Pragma("unroll") for (int k = 0; k < 2; ++k) dst[n][k] = *(const LAS bf16x8*)(lds + PG8_SB(b, h) + boff + n * 2048 + k * 1024); } while (0)
; #define PG8_MMA(ai, bj, At, Bt) do { __builtin_amdgcn_s_setprio(1); _Pragma("unroll") for (int m = 0; m < 4; ++m) _Pragma("unroll") for (int n = 0; n < 2; ++n) _Pragma("unroll") for (int k = 0; k < 2; ++k) \
;         acc[ai][bj][m][n] = __builtin_amdgcn_mfma_f32_16x16x32_bf16(Bt[n][k], At[m][k], acc[ai][bj][m][n], 0, 0, 0); __builtin_amdgcn_s_setprio(0); } while (0)
; #define PG8_WAIT_V(n) asm volatile("s_waitcnt vmcnt(" #n ")" ::: "memory")
; #define PG8_WAIT_L(n) asm volatile("s_waitcnt lgkmcnt(" #n ")" ::: "memory")
; #define PG8_BAR __builtin_amdgcn_s_barrier()
; #define PG8_SCHED __builtin_amdgcn_sched_barrier(0)
; template <class Epi, class Sched>
; __device__ __forceinline__ void gemm_phase(LAS unsigned char* lds, const Gemm g, const Sched& S, const Epi& E) {
;     ...
;             PG8_WAIT_V(6); PG8_BAR; PG8_MMA(1, 1, At, B1); PG8_BAR;
;             PG8_LDB(B0, 1, 0); PG8_SCHED; PG8_LDA(At, 1, 0); PG8_STAGE(PG8_SA(0, 1), a2 + hstep, voffA);
;             PG8_WAIT_L(8); PG8_BAR; PG8_WAIT_L(0); PG8_MMA(0, 0, At, B0); PG8_BAR; PG8_SCHED;
;             PG8_LDB(B1, 1, 1); PG8_STAGE(PG8_SB(1, 0), b3, voffB);
;             PG8_BAR; PG8_WAIT_L(0); PG8_MMA(0, 1, At, B1); PG8_BAR;
;             PG8_LDA(At, 1, 1); PG8_STAGE(PG8_SA(1, 0), a3, voffA);
.Lpw_p1_go:
	s_barrier
	s_setprio 1
	v_mfma_f32_16x16x32_bf16 v[58:61], v[200:203], v[168:171], 0
	v_mfma_f32_16x16x32_bf16 v[50:53], v[212:215], v[168:171], 0
	v_mfma_f32_16x16x32_bf16 v[42:45], v[200:203], v[176:179], 0
	v_mfma_f32_16x16x32_bf16 v[34:37], v[212:215], v[176:179], 0
	v_mfma_f32_16x16x32_bf16 v[26:29], v[200:203], v[184:187], 0
	v_mfma_f32_16x16x32_bf16 v[18:21], v[212:215], v[184:187], 0
	v_mfma_f32_16x16x32_bf16 v[10:13], v[200:203], v[192:195], 0
	v_mfma_f32_16x16x32_bf16 v[2:5], v[212:215], v[192:195], 0
	v_mfma_f32_16x16x32_bf16 v[58:61], v[208:211], v[172:175], v[58:61]
	v_mfma_f32_16x16x32_bf16 v[50:53], v[216:219], v[172:175], v[50:53]
	v_mfma_f32_16x16x32_bf16 v[42:45], v[208:211], v[180:183], v[42:45]
	v_mfma_f32_16x16x32_bf16 v[34:37], v[216:219], v[180:183], v[34:37]
	v_mfma_f32_16x16x32_bf16 v[26:29], v[208:211], v[188:191], v[26:29]
	v_mfma_f32_16x16x32_bf16 v[18:21], v[216:219], v[188:191], v[18:21]
	v_mfma_f32_16x16x32_bf16 v[10:13], v[208:211], v[196:199], v[10:13]
	v_mfma_f32_16x16x32_bf16 v[2:5], v[216:219], v[196:199], v[2:5]
	s_setprio 0
	s_add_i32 s52, 0, 0x18000
	v_add_u32_e32 v151, s52, v146
	s_barrier
	ds_read_b128 v[152:155], v151
	ds_read_b128 v[156:159], v151 offset:1024
	ds_read_b128 v[160:163], v151 offset:2048
	ds_read_b128 v[164:167], v151 offset:3072
	s_add_u32 s26, s26, 0x80000
	s_addc_u32 s27, s27, 0
	s_mov_b32 m0, s36
	v_lshl_add_u64 v[200:201], s[26:27], 0, v[130:131]
	ds_read_b128 v[168:171], v149 offset:32768
	ds_read_b128 v[172:175], v149 offset:33792
	ds_read_b128 v[176:179], v149 offset:34816
	ds_read_b128 v[180:183], v149 offset:35840
	ds_read_b128 v[184:187], v149 offset:36864
	ds_read_b128 v[188:191], v149 offset:37888
	ds_read_b128 v[192:195], v149 offset:38912
	ds_read_b128 v[196:199], v149 offset:39936
	global_load_lds_dwordx4 v[200:201], off
	v_lshl_add_u64 v[200:201], s[26:27], 0, v[134:135]
	s_mov_b32 m0, s37
	s_nop 0
	global_load_lds_dwordx4 v[200:201], off
	s_waitcnt lgkmcnt(8)
	s_barrier
	s_waitcnt lgkmcnt(0)
	s_setprio 1
	s_waitcnt lgkmcnt(0)
	v_mfma_f32_16x16x32_bf16 v[126:129], v[152:155], v[168:171], v[126:129]
	v_mfma_f32_16x16x32_bf16 v[118:121], v[160:163], v[168:171], v[118:121]
	v_mfma_f32_16x16x32_bf16 v[110:113], v[152:155], v[176:179], v[110:113]
	v_mfma_f32_16x16x32_bf16 v[102:105], v[160:163], v[176:179], v[102:105]
	v_mfma_f32_16x16x32_bf16 v[94:97], v[152:155], v[184:187], v[94:97]
	v_mfma_f32_16x16x32_bf16 v[86:89], v[160:163], v[184:187], v[86:89]
	v_mfma_f32_16x16x32_bf16 v[78:81], v[152:155], v[192:195], v[78:81]
	v_mfma_f32_16x16x32_bf16 v[70:73], v[160:163], v[192:195], v[70:73]
	v_mfma_f32_16x16x32_bf16 v[126:129], v[156:159], v[172:175], v[126:129]
	v_mfma_f32_16x16x32_bf16 v[118:121], v[164:167], v[172:175], v[118:121]
	v_mfma_f32_16x16x32_bf16 v[110:113], v[156:159], v[180:183], v[110:113]
	v_mfma_f32_16x16x32_bf16 v[102:105], v[164:167], v[180:183], v[102:105]
	v_mfma_f32_16x16x32_bf16 v[94:97], v[156:159], v[188:191], v[94:97]
	v_mfma_f32_16x16x32_bf16 v[86:89], v[164:167], v[188:191], v[86:89]
	v_mfma_f32_16x16x32_bf16 v[78:81], v[156:159], v[196:199], v[78:81]
	v_mfma_f32_16x16x32_bf16 v[70:73], v[164:167], v[196:199], v[70:73]
	s_setprio 0
	s_barrier
	s_add_i32 s26, 0, 0x1c000
	s_add_i32 s27, s52, s31
	v_add_u32_e32 v151, s26, v146
	v_lshl_add_u64 v[204:205], v[204:205], 0, s[6:7]
	s_mov_b32 m0, s27
	ds_read_b128 v[200:203], v151
	ds_read_b128 v[208:211], v151 offset:1024
	ds_read_b128 v[212:215], v151 offset:2048
	ds_read_b128 v[216:219], v151 offset:3072
	global_load_lds_dwordx4 v[204:205], off
	v_lshl_add_u64 v[204:205], v[220:221], 0, s[6:7]
	s_add_i32 m0, s27, 0x2000
	s_nop 0
	global_load_lds_dwordx4 v[204:205], off
	s_barrier
	s_waitcnt lgkmcnt(0)
	s_setprio 1
	s_waitcnt lgkmcnt(0)
	v_mfma_f32_16x16x32_bf16 v[122:125], v[200:203], v[168:171], v[122:125]
	v_mfma_f32_16x16x32_bf16 v[114:117], v[212:215], v[168:171], v[114:117]
	v_mfma_f32_16x16x32_bf16 v[106:109], v[200:203], v[176:179], v[106:109]
	v_mfma_f32_16x16x32_bf16 v[98:101], v[212:215], v[176:179], v[98:101]
	v_mfma_f32_16x16x32_bf16 v[90:93], v[200:203], v[184:187], v[90:93]
	v_mfma_f32_16x16x32_bf16 v[82:85], v[212:215], v[184:187], v[82:85]
	v_mfma_f32_16x16x32_bf16 v[74:77], v[200:203], v[192:195], v[74:77]
	v_mfma_f32_16x16x32_bf16 v[66:69], v[212:215], v[192:195], v[66:69]
	v_mfma_f32_16x16x32_bf16 v[122:125], v[208:211], v[172:175], v[122:125]
	v_mfma_f32_16x16x32_bf16 v[114:117], v[216:219], v[172:175], v[114:117]
	v_mfma_f32_16x16x32_bf16 v[106:109], v[208:211], v[180:183], v[106:109]
	v_mfma_f32_16x16x32_bf16 v[98:101], v[216:219], v[180:183], v[98:101]
	v_mfma_f32_16x16x32_bf16 v[90:93], v[208:211], v[188:191], v[90:93]
	v_mfma_f32_16x16x32_bf16 v[82:85], v[216:219], v[188:191], v[82:85]
	v_mfma_f32_16x16x32_bf16 v[74:77], v[208:211], v[196:199], v[74:77]
	v_mfma_f32_16x16x32_bf16 v[66:69], v[216:219], v[196:199], v[66:69]
	s_setprio 0
	s_mov_b32 m0, s40
	v_lshl_add_u64 v[204:205], v[222:223], 0, s[6:7]
	s_barrier
	ds_read_b128 v[168:171], v149 offset:49152
	ds_read_b128 v[172:175], v149 offset:50176
	ds_read_b128 v[176:179], v149 offset:51200
	ds_read_b128 v[180:183], v149 offset:52224
	ds_read_b128 v[184:187], v149 offset:53248
	ds_read_b128 v[188:191], v149 offset:54272
	ds_read_b128 v[192:195], v149 offset:55296
	ds_read_b128 v[196:199], v149 offset:56320
	global_load_lds_dwordx4 v[204:205], off
	v_lshl_add_u64 v[204:205], v[224:225], 0, s[6:7]
	s_mov_b32 m0, s41
	s_nop 0
	global_load_lds_dwordx4 v[204:205], off
	s_barrier
; #define PG8_STAGE(bufoff, gbase, voff) do { _Pragma("unroll") for (int _i = 0; _i < 2; ++_i) \
;         __builtin_amdgcn_global_load_lds((const unsigned*)((const char*)(gbase) + (voff)[_i]), (LAS unsigned*)(lds + (bufoff) + ldsw + _i * 8192), 16, 0, 0); } while (0)
; #define PG8_LDA(dst, b, h) do { _Pragma("unroll") for (int m = 0; m < 4; ++m) _Pragma("unroll") for (int k = 0; k < 2; ++k) dst[m][k] = *(const LAS bf16x8*)(lds + PG8_SA(b, h) + aoff + m * 2048 + k * 1024); } while (0)
; #define PG8_LDB(dst, b, h) do { _Pragma("unroll") for (int n = 0; n < 2; ++n) _Pragma("unroll") for (int k = 0; k < 2; ++k) dst[n][k] = *(const LAS bf16x8*)(lds + PG8_SB(b, h) + boff + n * 2048 + k * 1024); } while (0)
; #define PG8_MMA(ai, bj, At, Bt) do { __builtin_amdgcn_s_setprio(1); _Pragma("unroll") for (int m = 0; m < 4; ++m) _Pragma("unroll") for (int n = 0; n < 2; ++n) _Pragma("unroll") for (int k = 0; k < 2; ++k) \
;         acc[ai][bj][m][n] = __builtin_amdgcn_mfma_f32_16x16x32_bf16(Bt[n][k], At[m][k], acc[ai][bj][m][n], 0, 0, 0); __builtin_amdgcn_s_setprio(0); } while (0)
; #define PG8_WAIT_V(n) asm volatile("s_waitcnt vmcnt(" #n ")" ::: "memory")
; #define PG8_WAIT_L(n) asm volatile("s_waitcnt lgkmcnt(" #n ")" ::: "memory")
; #define PG8_BAR __builtin_amdgcn_s_barrier()
; #define PG8_SCHED __builtin_amdgcn_sched_barrier(0)
; template <class Epi, class Sched>
; __device__ __forceinline__ void gemm_phase(LAS unsigned char* lds, const Gemm g, const Sched& S, const Epi& E) {
;     ...
;             PG8_LDB(B0, 0, 0); PG8_SCHED; PG8_LDA(At, 0, 0); PG8_STAGE(PG8_SA(1, 1), a1 + hstep, voffA);
;             PG8_WAIT_L(8); PG8_BAR; PG8_WAIT_L(0); PG8_MMA(0, 0, At, B0); PG8_BAR; PG8_SCHED;
;             PG8_LDB(B1, 0, 1); PG8_STAGE(PG8_SB(0, 0), b2, voffB);
;     ...
;             PG8_BAR; PG8_WAIT_L(0); PG8_MMA(0, 1, At, B1); PG8_BAR;
;             PG8_LDA(At, 1, 1); PG8_STAGE(PG8_SA(1, 0), a3, voffA);
;             PG8_BAR; PG8_WAIT_L(0); PG8_MMA(1, 0, At, B0); PG8_BAR; PG8_SCHED;
;             PG8_STAGE(PG8_SB(1, 1), b3 + hstep, voffB);
;             PG8_WAIT_V(6); PG8_BAR; PG8_MMA(1, 1, At, B1); PG8_BAR;
	s_waitcnt lgkmcnt(0)
	s_setprio 1
	s_waitcnt lgkmcnt(0)
	v_mfma_f32_16x16x32_bf16 v[62:65], v[152:155], v[168:171], v[62:65]
	v_mfma_f32_16x16x32_bf16 v[54:57], v[160:163], v[168:171], v[54:57]
	v_mfma_f32_16x16x32_bf16 v[46:49], v[152:155], v[176:179], v[46:49]
	v_mfma_f32_16x16x32_bf16 v[38:41], v[160:163], v[176:179], v[38:41]
	v_mfma_f32_16x16x32_bf16 v[30:33], v[152:155], v[184:187], v[30:33]
	v_mfma_f32_16x16x32_bf16 v[22:25], v[160:163], v[184:187], v[22:25]
	v_mfma_f32_16x16x32_bf16 v[14:17], v[152:155], v[192:195], v[14:17]
	v_mfma_f32_16x16x32_bf16 v[6:9], v[160:163], v[192:195], v[6:9]
	v_mfma_f32_16x16x32_bf16 v[62:65], v[156:159], v[172:175], v[62:65]
	v_mfma_f32_16x16x32_bf16 v[54:57], v[164:167], v[172:175], v[54:57]
	v_mfma_f32_16x16x32_bf16 v[46:49], v[156:159], v[180:183], v[46:49]
	v_mfma_f32_16x16x32_bf16 v[38:41], v[164:167], v[180:183], v[38:41]
	v_mfma_f32_16x16x32_bf16 v[30:33], v[156:159], v[188:191], v[30:33]
	v_mfma_f32_16x16x32_bf16 v[22:25], v[164:167], v[188:191], v[22:25]
	v_mfma_f32_16x16x32_bf16 v[14:17], v[156:159], v[196:199], v[14:17]
	v_mfma_f32_16x16x32_bf16 v[6:9], v[164:167], v[196:199], v[6:9]
	s_setprio 0
	s_barrier
	s_add_u32 s24, s24, 0x80080
	s_addc_u32 s25, s25, 0
	s_add_i32 s26, s26, s31
	v_lshl_add_u64 v[152:153], s[24:25], 0, v[132:133]
	s_mov_b32 m0, s26
	s_nop 0
	global_load_lds_dwordx4 v[152:153], off
	v_lshl_add_u64 v[152:153], s[24:25], 0, v[136:137]
	s_add_i32 m0, s26, 0x2000
	s_nop 0
	global_load_lds_dwordx4 v[152:153], off
	s_waitcnt vmcnt(6)
	s_barrier
	s_setprio 1
	v_mfma_f32_16x16x32_bf16 v[58:61], v[200:203], v[168:171], v[58:61]
	v_mfma_f32_16x16x32_bf16 v[50:53], v[212:215], v[168:171], v[50:53]
	v_mfma_f32_16x16x32_bf16 v[42:45], v[200:203], v[176:179], v[42:45]
	v_mfma_f32_16x16x32_bf16 v[34:37], v[212:215], v[176:179], v[34:37]
	v_mfma_f32_16x16x32_bf16 v[26:29], v[200:203], v[184:187], v[26:29]
	v_mfma_f32_16x16x32_bf16 v[18:21], v[212:215], v[184:187], v[18:21]
	v_mfma_f32_16x16x32_bf16 v[10:13], v[200:203], v[192:195], v[10:13]
	v_mfma_f32_16x16x32_bf16 v[2:5], v[212:215], v[192:195], v[2:5]
	v_mfma_f32_16x16x32_bf16 v[58:61], v[208:211], v[172:175], v[58:61]
	v_mfma_f32_16x16x32_bf16 v[50:53], v[216:219], v[172:175], v[50:53]
	v_mfma_f32_16x16x32_bf16 v[42:45], v[208:211], v[180:183], v[42:45]
	v_mfma_f32_16x16x32_bf16 v[34:37], v[216:219], v[180:183], v[34:37]
	v_mfma_f32_16x16x32_bf16 v[26:29], v[208:211], v[188:191], v[26:29]
	v_mfma_f32_16x16x32_bf16 v[18:21], v[216:219], v[188:191], v[18:21]
	v_mfma_f32_16x16x32_bf16 v[10:13], v[208:211], v[196:199], v[10:13]
	v_mfma_f32_16x16x32_bf16 v[2:5], v[216:219], v[196:199], v[2:5]
	s_setprio 0
	s_add_i32 s51, s51, 2
	s_add_u32 s22, s22, 0x100
	s_addc_u32 s23, s23, 0
	s_add_u32 s49, s49, 0x100
	s_addc_u32 s50, s50, 0
	s_cmp_gt_u32 s51, 29
	s_barrier
.LBB0_243:
	ds_read_b128 v[152:155], v148
	ds_read_b128 v[156:159], v148 offset:1024
	ds_read_b128 v[160:163], v148 offset:2048
	ds_read_b128 v[164:167], v148 offset:3072
	s_add_u32 s24, s22, 0xfff80080
	s_addc_u32 s25, s23, -1
	s_cmp_eq_u32 s51, 28
	s_cselect_b32 s27, s15, s25
	s_cselect_b32 s26, s47, s24
	s_cselect_b32 s25, s9, s50
	s_cselect_b32 s24, s48, s49
	v_lshl_add_u64 v[200:201], s[22:23], 0, v[138:139]
	s_add_i32 m0, s21, 0xc000
	ds_read_b128 v[168:171], v149
	ds_read_b128 v[172:175], v149 offset:1024
	ds_read_b128 v[176:179], v149 offset:2048
	ds_read_b128 v[180:183], v149 offset:3072
	ds_read_b128 v[184:187], v149 offset:4096
	ds_read_b128 v[188:191], v149 offset:5120
	ds_read_b128 v[192:195], v149 offset:6144
	ds_read_b128 v[196:199], v149 offset:7168
	global_load_lds_dwordx4 v[200:201], off
	v_lshl_add_u64 v[200:201], s[22:23], 0, v[140:141]
	s_add_i32 m0, s21, 0xe000
	s_nop 0
	global_load_lds_dwordx4 v[200:201], off
	s_waitcnt lgkmcnt(8)
	s_barrier
	s_waitcnt lgkmcnt(0)
	s_setprio 1
	s_waitcnt lgkmcnt(0)
	v_mfma_f32_16x16x32_bf16 v[126:129], v[152:155], v[168:171], v[126:129]
	v_mfma_f32_16x16x32_bf16 v[118:121], v[160:163], v[168:171], v[118:121]
	v_mfma_f32_16x16x32_bf16 v[110:113], v[152:155], v[176:179], v[110:113]
	v_mfma_f32_16x16x32_bf16 v[102:105], v[160:163], v[176:179], v[102:105]
	v_mfma_f32_16x16x32_bf16 v[94:97], v[152:155], v[184:187], v[94:97]
	v_mfma_f32_16x16x32_bf16 v[86:89], v[160:163], v[184:187], v[86:89]
	v_mfma_f32_16x16x32_bf16 v[78:81], v[152:155], v[192:195], v[78:81]
	v_mfma_f32_16x16x32_bf16 v[70:73], v[160:163], v[192:195], v[70:73]
	v_mfma_f32_16x16x32_bf16 v[126:129], v[156:159], v[172:175], v[126:129]
	v_mfma_f32_16x16x32_bf16 v[118:121], v[164:167], v[172:175], v[118:121]
	v_mfma_f32_16x16x32_bf16 v[110:113], v[156:159], v[180:183], v[110:113]
	v_mfma_f32_16x16x32_bf16 v[102:105], v[164:167], v[180:183], v[102:105]
	v_mfma_f32_16x16x32_bf16 v[94:97], v[156:159], v[188:191], v[94:97]
	v_mfma_f32_16x16x32_bf16 v[86:89], v[164:167], v[188:191], v[86:89]
	v_mfma_f32_16x16x32_bf16 v[78:81], v[156:159], v[196:199], v[78:81]
	v_mfma_f32_16x16x32_bf16 v[70:73], v[164:167], v[196:199], v[70:73]
	s_setprio 0
	s_barrier
	s_add_i32 s52, s43, s31
	v_lshl_add_u64 v[204:205], s[24:25], 0, v[132:133]
	s_mov_b32 m0, s52
	ds_read_b128 v[200:203], v150
	ds_read_b128 v[208:211], v150 offset:1024
	ds_read_b128 v[212:215], v150 offset:2048
	ds_read_b128 v[216:219], v150 offset:3072
	global_load_lds_dwordx4 v[204:205], off
	v_lshl_add_u64 v[220:221], s[24:25], 0, v[136:137]
	s_add_i32 m0, s52, 0x2000
	s_nop 0
	global_load_lds_dwordx4 v[220:221], off
	s_barrier
; #define PG8_STAGE(bufoff, gbase, voff) do { _Pragma("unroll") for (int _i = 0; _i < 2; ++_i) \
;         __builtin_amdgcn_global_load_lds((const unsigned*)((const char*)(gbase) + (voff)[_i]), (LAS unsigned*)(lds + (bufoff) + ldsw + _i * 8192), 16, 0, 0); } while (0)
; #define PG8_LDA(dst, b, h) do { _Pragma("unroll") for (int m = 0; m < 4; ++m) _Pragma("unroll") for (int k = 0; k < 2; ++k) dst[m][k] = *(const LAS bf16x8*)(lds + PG8_SA(b, h) + aoff + m * 2048 + k * 1024); } while (0)
; #define PG8_LDB(dst, b, h) do { _Pragma("unroll") for (int n = 0; n < 2; ++n) _Pragma("unroll") for (int k = 0; k < 2; ++k) dst[n][k] = *(const LAS bf16x8*)(lds + PG8_SB(b, h) + boff + n * 2048 + k * 1024); } while (0)
; #define PG8_MMA(ai, bj, At, Bt) do { __builtin_amdgcn_s_setprio(1); _Pragma("unroll") for (int m = 0; m < 4; ++m) _Pragma("unroll") for (int n = 0; n < 2; ++n) _Pragma("unroll") for (int k = 0; k < 2; ++k) \
;         acc[ai][bj][m][n] = __builtin_amdgcn_mfma_f32_16x16x32_bf16(Bt[n][k], At[m][k], acc[ai][bj][m][n], 0, 0, 0); __builtin_amdgcn_s_setprio(0); } while (0)
; #define PG8_WAIT_V(n) asm volatile("s_waitcnt vmcnt(" #n ")" ::: "memory")
; #define PG8_WAIT_L(n) asm volatile("s_waitcnt lgkmcnt(" #n ")" ::: "memory")
; #define PG8_BAR __builtin_amdgcn_s_barrier()
; #define PG8_SCHED __builtin_amdgcn_sched_barrier(0)
; template <class Epi, class Sched>
; __device__ __forceinline__ void gemm_phase(LAS unsigned char* lds, const Gemm g, const Sched& S, const Epi& E) {
;     ...
;             PG8_BAR; PG8_WAIT_L(0); PG8_MMA(0, 1, At, B1); PG8_BAR;
;             PG8_LDA(At, 0, 1); PG8_STAGE(PG8_SA(0, 0), a2, voffA);
;             PG8_BAR; PG8_WAIT_L(0); PG8_MMA(1, 0, At, B0); PG8_BAR; PG8_SCHED;
;             PG8_STAGE(PG8_SB(0, 1), b2 + hstep, voffB);
;             PG8_WAIT_V(6); PG8_BAR; PG8_MMA(1, 1, At, B1); PG8_BAR;
;             PG8_LDB(B0, 1, 0); PG8_SCHED; PG8_LDA(At, 1, 0); PG8_STAGE(PG8_SA(0, 1), a2 + hstep, voffA);
;             PG8_WAIT_L(8); PG8_BAR; PG8_WAIT_L(0); PG8_MMA(0, 0, At, B0); PG8_BAR; PG8_SCHED;
	s_waitcnt lgkmcnt(0)
	s_setprio 1
	s_waitcnt lgkmcnt(0)
	v_mfma_f32_16x16x32_bf16 v[122:125], v[200:203], v[168:171], v[122:125]
	v_mfma_f32_16x16x32_bf16 v[114:117], v[212:215], v[168:171], v[114:117]
	v_mfma_f32_16x16x32_bf16 v[106:109], v[200:203], v[176:179], v[106:109]
	v_mfma_f32_16x16x32_bf16 v[98:101], v[212:215], v[176:179], v[98:101]
	v_mfma_f32_16x16x32_bf16 v[90:93], v[200:203], v[184:187], v[90:93]
	v_mfma_f32_16x16x32_bf16 v[82:85], v[212:215], v[184:187], v[82:85]
	v_mfma_f32_16x16x32_bf16 v[74:77], v[200:203], v[192:195], v[74:77]
	v_mfma_f32_16x16x32_bf16 v[66:69], v[212:215], v[192:195], v[66:69]
	v_mfma_f32_16x16x32_bf16 v[122:125], v[208:211], v[172:175], v[122:125]
	v_mfma_f32_16x16x32_bf16 v[114:117], v[216:219], v[172:175], v[114:117]
	v_mfma_f32_16x16x32_bf16 v[106:109], v[208:211], v[180:183], v[106:109]
	v_mfma_f32_16x16x32_bf16 v[98:101], v[216:219], v[180:183], v[98:101]
	v_mfma_f32_16x16x32_bf16 v[90:93], v[208:211], v[188:191], v[90:93]
	v_mfma_f32_16x16x32_bf16 v[82:85], v[216:219], v[188:191], v[82:85]
	v_mfma_f32_16x16x32_bf16 v[74:77], v[208:211], v[196:199], v[74:77]
	v_mfma_f32_16x16x32_bf16 v[66:69], v[216:219], v[196:199], v[66:69]
	s_setprio 0
	s_mov_b32 m0, s21
	v_lshl_add_u64 v[222:223], s[26:27], 0, v[130:131]
	s_barrier
	ds_read_b128 v[168:171], v149 offset:16384
	ds_read_b128 v[172:175], v149 offset:17408
	ds_read_b128 v[176:179], v149 offset:18432
	ds_read_b128 v[180:183], v149 offset:19456
	ds_read_b128 v[184:187], v149 offset:20480
	ds_read_b128 v[188:191], v149 offset:21504
	ds_read_b128 v[192:195], v149 offset:22528
	ds_read_b128 v[196:199], v149 offset:23552
	global_load_lds_dwordx4 v[222:223], off
	v_lshl_add_u64 v[224:225], s[26:27], 0, v[134:135]
	s_mov_b32 m0, s35
	s_nop 0
	global_load_lds_dwordx4 v[224:225], off
	s_barrier
	s_waitcnt lgkmcnt(0)
	s_setprio 1
	s_waitcnt lgkmcnt(0)
	v_mfma_f32_16x16x32_bf16 v[62:65], v[152:155], v[168:171], v[62:65]
	v_mfma_f32_16x16x32_bf16 v[54:57], v[160:163], v[168:171], v[54:57]
	v_mfma_f32_16x16x32_bf16 v[46:49], v[152:155], v[176:179], v[46:49]
	v_mfma_f32_16x16x32_bf16 v[38:41], v[160:163], v[176:179], v[38:41]
	v_mfma_f32_16x16x32_bf16 v[30:33], v[152:155], v[184:187], v[30:33]
	v_mfma_f32_16x16x32_bf16 v[22:25], v[160:163], v[184:187], v[22:25]
	v_mfma_f32_16x16x32_bf16 v[14:17], v[152:155], v[192:195], v[14:17]
	v_mfma_f32_16x16x32_bf16 v[6:9], v[160:163], v[192:195], v[6:9]
	v_mfma_f32_16x16x32_bf16 v[62:65], v[156:159], v[172:175], v[62:65]
	v_mfma_f32_16x16x32_bf16 v[54:57], v[164:167], v[172:175], v[54:57]
	v_mfma_f32_16x16x32_bf16 v[46:49], v[156:159], v[180:183], v[46:49]
	v_mfma_f32_16x16x32_bf16 v[38:41], v[164:167], v[180:183], v[38:41]
	v_mfma_f32_16x16x32_bf16 v[30:33], v[156:159], v[188:191], v[30:33]
	v_mfma_f32_16x16x32_bf16 v[22:25], v[164:167], v[188:191], v[22:25]
	v_mfma_f32_16x16x32_bf16 v[14:17], v[156:159], v[196:199], v[14:17]
	v_mfma_f32_16x16x32_bf16 v[6:9], v[164:167], v[196:199], v[6:9]
	s_setprio 0
	s_barrier
	s_add_u32 s52, s24, 0x80000
	s_addc_u32 s53, s25, 0
	s_add_i32 s54, s44, s31
	v_lshl_add_u64 v[152:153], s[52:53], 0, v[132:133]
	s_mov_b32 m0, s54
	s_nop 0
	global_load_lds_dwordx4 v[152:153], off
	v_lshl_add_u64 v[152:153], s[52:53], 0, v[136:137]
	s_add_i32 m0, s54, 0x2000
	s_nop 0
	global_load_lds_dwordx4 v[152:153], off
	s_waitcnt vmcnt(6)
	s_barrier
	s_setprio 1
	v_mfma_f32_16x16x32_bf16 v[58:61], v[200:203], v[168:171], v[58:61]
	v_mfma_f32_16x16x32_bf16 v[50:53], v[212:215], v[168:171], v[50:53]
	v_mfma_f32_16x16x32_bf16 v[42:45], v[200:203], v[176:179], v[42:45]
	v_mfma_f32_16x16x32_bf16 v[34:37], v[212:215], v[176:179], v[34:37]
	v_mfma_f32_16x16x32_bf16 v[26:29], v[200:203], v[184:187], v[26:29]
	v_mfma_f32_16x16x32_bf16 v[18:21], v[212:215], v[184:187], v[18:21]
	v_mfma_f32_16x16x32_bf16 v[10:13], v[200:203], v[192:195], v[10:13]
	v_mfma_f32_16x16x32_bf16 v[2:5], v[212:215], v[192:195], v[2:5]
	v_mfma_f32_16x16x32_bf16 v[58:61], v[208:211], v[172:175], v[58:61]
	v_mfma_f32_16x16x32_bf16 v[50:53], v[216:219], v[172:175], v[50:53]
	v_mfma_f32_16x16x32_bf16 v[42:45], v[208:211], v[180:183], v[42:45]
	v_mfma_f32_16x16x32_bf16 v[34:37], v[216:219], v[180:183], v[34:37]
	v_mfma_f32_16x16x32_bf16 v[26:29], v[208:211], v[188:191], v[26:29]
	v_mfma_f32_16x16x32_bf16 v[18:21], v[216:219], v[188:191], v[18:21]
	v_mfma_f32_16x16x32_bf16 v[10:13], v[208:211], v[196:199], v[10:13]
	v_mfma_f32_16x16x32_bf16 v[2:5], v[216:219], v[196:199], v[2:5]
	s_setprio 0
	s_add_i32 s52, 0, 0x18000
	v_add_u32_e32 v151, s52, v146
	s_barrier
	ds_read_b128 v[152:155], v151
	ds_read_b128 v[156:159], v151 offset:1024
	ds_read_b128 v[160:163], v151 offset:2048
	ds_read_b128 v[164:167], v151 offset:3072
	s_add_u32 s26, s26, 0x80000
	s_addc_u32 s27, s27, 0
	s_mov_b32 m0, s36
	v_lshl_add_u64 v[200:201], s[26:27], 0, v[130:131]
	ds_read_b128 v[168:171], v149 offset:32768
	ds_read_b128 v[172:175], v149 offset:33792
	ds_read_b128 v[176:179], v149 offset:34816
	ds_read_b128 v[180:183], v149 offset:35840
	ds_read_b128 v[184:187], v149 offset:36864
	ds_read_b128 v[188:191], v149 offset:37888
	ds_read_b128 v[192:195], v149 offset:38912
	ds_read_b128 v[196:199], v149 offset:39936
	global_load_lds_dwordx4 v[200:201], off
	v_lshl_add_u64 v[200:201], s[26:27], 0, v[134:135]
	s_mov_b32 m0, s37
	s_nop 0
	global_load_lds_dwordx4 v[200:201], off
	s_waitcnt lgkmcnt(8)
	s_barrier
; #define PG8_STAGE(bufoff, gbase, voff) do { _Pragma("unroll") for (int _i = 0; _i < 2; ++_i) \
;         __builtin_amdgcn_global_load_lds((const unsigned*)((const char*)(gbase) + (voff)[_i]), (LAS unsigned*)(lds + (bufoff) + ldsw + _i * 8192), 16, 0, 0); } while (0)
; #define PG8_LDA(dst, b, h) do { _Pragma("unroll") for (int m = 0; m < 4; ++m) _Pragma("unroll") for (int k = 0; k < 2; ++k) dst[m][k] = *(const LAS bf16x8*)(lds + PG8_SA(b, h) + aoff + m * 2048 + k * 1024); } while (0)
; #define PG8_LDB(dst, b, h) do { _Pragma("unroll") for (int n = 0; n < 2; ++n) _Pragma("unroll") for (int k = 0; k < 2; ++k) dst[n][k] = *(const LAS bf16x8*)(lds + PG8_SB(b, h) + boff + n * 2048 + k * 1024); } while (0)
; #define PG8_MMA(ai, bj, At, Bt) do { __builtin_amdgcn_s_setprio(1); _Pragma("unroll") for (int m = 0; m < 4; ++m) _Pragma("unroll") for (int n = 0; n < 2; ++n) _Pragma("unroll") for (int k = 0; k < 2; ++k) \
;         acc[ai][bj][m][n] = __builtin_amdgcn_mfma_f32_16x16x32_bf16(Bt[n][k], At[m][k], acc[ai][bj][m][n], 0, 0, 0); __builtin_amdgcn_s_setprio(0); } while (0)
; #define PG8_WAIT_V(n) asm volatile("s_waitcnt vmcnt(" #n ")" ::: "memory")
; #define PG8_WAIT_L(n) asm volatile("s_waitcnt lgkmcnt(" #n ")" ::: "memory")
; #define PG8_BAR __builtin_amdgcn_s_barrier()
; #define PG8_SCHED __builtin_amdgcn_sched_barrier(0)
; template <class Epi, class Sched>
; __device__ __forceinline__ void gemm_phase(LAS unsigned char* lds, const Gemm g, const Sched& S, const Epi& E) {
;     ...
;             PG8_WAIT_L(8); PG8_BAR; PG8_WAIT_L(0); PG8_MMA(0, 0, At, B0); PG8_BAR; PG8_SCHED;
;             PG8_LDB(B1, 1, 1); PG8_STAGE(PG8_SB(1, 0), b3, voffB);
;             PG8_BAR; PG8_WAIT_L(0); PG8_MMA(0, 1, At, B1); PG8_BAR;
;             PG8_LDA(At, 1, 1); PG8_STAGE(PG8_SA(1, 0), a3, voffA);
;             PG8_BAR; PG8_WAIT_L(0); PG8_MMA(1, 0, At, B0); PG8_BAR; PG8_SCHED;
;             PG8_STAGE(PG8_SB(1, 1), b3 + hstep, voffB);
;             PG8_WAIT_V(6); PG8_BAR; PG8_MMA(1, 1, At, B1); PG8_BAR;
	s_waitcnt lgkmcnt(0)
	s_setprio 1
	s_waitcnt lgkmcnt(0)
	v_mfma_f32_16x16x32_bf16 v[126:129], v[152:155], v[168:171], v[126:129]
	v_mfma_f32_16x16x32_bf16 v[118:121], v[160:163], v[168:171], v[118:121]
	v_mfma_f32_16x16x32_bf16 v[110:113], v[152:155], v[176:179], v[110:113]
	v_mfma_f32_16x16x32_bf16 v[102:105], v[160:163], v[176:179], v[102:105]
	v_mfma_f32_16x16x32_bf16 v[94:97], v[152:155], v[184:187], v[94:97]
	v_mfma_f32_16x16x32_bf16 v[86:89], v[160:163], v[184:187], v[86:89]
	v_mfma_f32_16x16x32_bf16 v[78:81], v[152:155], v[192:195], v[78:81]
	v_mfma_f32_16x16x32_bf16 v[70:73], v[160:163], v[192:195], v[70:73]
	v_mfma_f32_16x16x32_bf16 v[126:129], v[156:159], v[172:175], v[126:129]
	v_mfma_f32_16x16x32_bf16 v[118:121], v[164:167], v[172:175], v[118:121]
	v_mfma_f32_16x16x32_bf16 v[110:113], v[156:159], v[180:183], v[110:113]
	v_mfma_f32_16x16x32_bf16 v[102:105], v[164:167], v[180:183], v[102:105]
	v_mfma_f32_16x16x32_bf16 v[94:97], v[156:159], v[188:191], v[94:97]
	v_mfma_f32_16x16x32_bf16 v[86:89], v[164:167], v[188:191], v[86:89]
	v_mfma_f32_16x16x32_bf16 v[78:81], v[156:159], v[196:199], v[78:81]
	v_mfma_f32_16x16x32_bf16 v[70:73], v[164:167], v[196:199], v[70:73]
	s_setprio 0
	s_barrier
	s_add_i32 s26, 0, 0x1c000
	s_add_i32 s27, s52, s31
	v_add_u32_e32 v151, s26, v146
	v_lshl_add_u64 v[204:205], v[204:205], 0, s[6:7]
	s_mov_b32 m0, s27
	ds_read_b128 v[200:203], v151
	ds_read_b128 v[208:211], v151 offset:1024
	ds_read_b128 v[212:215], v151 offset:2048
	ds_read_b128 v[216:219], v151 offset:3072
	global_load_lds_dwordx4 v[204:205], off
	v_lshl_add_u64 v[204:205], v[220:221], 0, s[6:7]
	s_add_i32 m0, s27, 0x2000
	s_nop 0
	global_load_lds_dwordx4 v[204:205], off
	s_barrier
	s_waitcnt lgkmcnt(0)
	s_setprio 1
	s_waitcnt lgkmcnt(0)
	v_mfma_f32_16x16x32_bf16 v[122:125], v[200:203], v[168:171], v[122:125]
	v_mfma_f32_16x16x32_bf16 v[114:117], v[212:215], v[168:171], v[114:117]
	v_mfma_f32_16x16x32_bf16 v[106:109], v[200:203], v[176:179], v[106:109]
	v_mfma_f32_16x16x32_bf16 v[98:101], v[212:215], v[176:179], v[98:101]
	v_mfma_f32_16x16x32_bf16 v[90:93], v[200:203], v[184:187], v[90:93]
	v_mfma_f32_16x16x32_bf16 v[82:85], v[212:215], v[184:187], v[82:85]
	v_mfma_f32_16x16x32_bf16 v[74:77], v[200:203], v[192:195], v[74:77]
	v_mfma_f32_16x16x32_bf16 v[66:69], v[212:215], v[192:195], v[66:69]
	v_mfma_f32_16x16x32_bf16 v[122:125], v[208:211], v[172:175], v[122:125]
	v_mfma_f32_16x16x32_bf16 v[114:117], v[216:219], v[172:175], v[114:117]
	v_mfma_f32_16x16x32_bf16 v[106:109], v[208:211], v[180:183], v[106:109]
	v_mfma_f32_16x16x32_bf16 v[98:101], v[216:219], v[180:183], v[98:101]
	v_mfma_f32_16x16x32_bf16 v[90:93], v[208:211], v[188:191], v[90:93]
	v_mfma_f32_16x16x32_bf16 v[82:85], v[216:219], v[188:191], v[82:85]
	v_mfma_f32_16x16x32_bf16 v[74:77], v[208:211], v[196:199], v[74:77]
	v_mfma_f32_16x16x32_bf16 v[66:69], v[216:219], v[196:199], v[66:69]
	s_setprio 0
	s_mov_b32 m0, s40
	v_lshl_add_u64 v[204:205], v[222:223], 0, s[6:7]
	s_barrier
	ds_read_b128 v[168:171], v149 offset:49152
	ds_read_b128 v[172:175], v149 offset:50176
	ds_read_b128 v[176:179], v149 offset:51200
	ds_read_b128 v[180:183], v149 offset:52224
	ds_read_b128 v[184:187], v149 offset:53248
	ds_read_b128 v[188:191], v149 offset:54272
	ds_read_b128 v[192:195], v149 offset:55296
	ds_read_b128 v[196:199], v149 offset:56320
	global_load_lds_dwordx4 v[204:205], off
	v_lshl_add_u64 v[204:205], v[224:225], 0, s[6:7]
	s_mov_b32 m0, s41
	s_nop 0
	global_load_lds_dwordx4 v[204:205], off
	s_barrier
	s_waitcnt lgkmcnt(0)
	s_setprio 1
	s_waitcnt lgkmcnt(0)
	v_mfma_f32_16x16x32_bf16 v[62:65], v[152:155], v[168:171], v[62:65]
	v_mfma_f32_16x16x32_bf16 v[54:57], v[160:163], v[168:171], v[54:57]
	v_mfma_f32_16x16x32_bf16 v[46:49], v[152:155], v[176:179], v[46:49]
	v_mfma_f32_16x16x32_bf16 v[38:41], v[160:163], v[176:179], v[38:41]
	v_mfma_f32_16x16x32_bf16 v[30:33], v[152:155], v[184:187], v[30:33]
	v_mfma_f32_16x16x32_bf16 v[22:25], v[160:163], v[184:187], v[22:25]
	v_mfma_f32_16x16x32_bf16 v[14:17], v[152:155], v[192:195], v[14:17]
	v_mfma_f32_16x16x32_bf16 v[6:9], v[160:163], v[192:195], v[6:9]
	v_mfma_f32_16x16x32_bf16 v[62:65], v[156:159], v[172:175], v[62:65]
	v_mfma_f32_16x16x32_bf16 v[54:57], v[164:167], v[172:175], v[54:57]
	v_mfma_f32_16x16x32_bf16 v[46:49], v[156:159], v[180:183], v[46:49]
	v_mfma_f32_16x16x32_bf16 v[38:41], v[164:167], v[180:183], v[38:41]
	v_mfma_f32_16x16x32_bf16 v[30:33], v[156:159], v[188:191], v[30:33]
	v_mfma_f32_16x16x32_bf16 v[22:25], v[164:167], v[188:191], v[22:25]
	v_mfma_f32_16x16x32_bf16 v[14:17], v[156:159], v[196:199], v[14:17]
	v_mfma_f32_16x16x32_bf16 v[6:9], v[164:167], v[196:199], v[6:9]
	s_setprio 0
	s_barrier
	s_add_u32 s24, s24, 0x80080
	s_addc_u32 s25, s25, 0
	s_add_i32 s26, s26, s31
	v_lshl_add_u64 v[152:153], s[24:25], 0, v[132:133]
	s_mov_b32 m0, s26
	s_nop 0
	global_load_lds_dwordx4 v[152:153], off
	v_lshl_add_u64 v[152:153], s[24:25], 0, v[136:137]
	s_add_i32 m0, s26, 0x2000
	s_nop 0
	global_load_lds_dwordx4 v[152:153], off
	s_cmp_eq_u32 s51, 28
	s_cbranch_scc0 .Lxs_p1_n
	s_add_u32 s24, s47, 0x80080
	s_addc_u32 s25, s15, 0
	v_lshl_add_u64 v[152:153], s[24:25], 0, v[138:139]
	s_add_i32 m0, s21, 0xc000
	s_nop 0
	global_load_lds_dwordx4 v[152:153], off
	v_lshl_add_u64 v[152:153], s[24:25], 0, v[140:141]
	s_add_i32 m0, s21, 0xe000
	s_nop 0
	global_load_lds_dwordx4 v[152:153], off
	s_waitcnt vmcnt(8)
	s_branch .Lxs_p1_j

; #define LAS __attribute__((address_space(3)))
; DI unsigned pk2(float a, float b) { f32x2_t v = {a, b}; return __builtin_bit_cast(unsigned, __builtin_convertvector(v, bf16x2_t)); }
; #define PG8_MMA(ai, bj, At, Bt) do { __builtin_amdgcn_s_setprio(1); _Pragma("unroll") for (int m = 0; m < 4; ++m) _Pragma("unroll") for (int n = 0; n < 2; ++n) _Pragma("unroll") for (int k = 0; k < 2; ++k) \
;         acc[ai][bj][m][n] = __builtin_amdgcn_mfma_f32_16x16x32_bf16(Bt[n][k], At[m][k], acc[ai][bj][m][n], 0, 0, 0); __builtin_amdgcn_s_setprio(0); } while (0)
; #define PG8_WAIT_V(n) asm volatile("s_waitcnt vmcnt(" #n ")" ::: "memory")
; #define PG8_BAR __builtin_amdgcn_s_barrier()
; template <class Epi, class Sched>
; __device__ __forceinline__ void gemm_phase(LAS unsigned char* lds, const Gemm g, const Sched& S, const Epi& E) {
;     ...
;             PG8_WAIT_V(6); PG8_BAR; PG8_MMA(1, 1, At, B1); PG8_BAR;
;         }
;     DI void operator()(const f32x4 (&acc)[2][2][4][2], const pg8::Unit& u, int wr, int wc, int fr, int fq, int ui, LAS unsigned char* lds) const {
;         const int row0 = u.pm * 256 + wr * 64 + fr, col0 = u.pn * 128 + wc * 32 + 8 * fq;
; #pragma unroll
;         for (int ai = 0; ai < 2; ++ai)
; #pragma unroll
;             for (int m = 0; m < 4; ++m) {
;                 const float rs = ss ? ((const LAS float*)(lds + 131072))[ui * 256 + wr * 64 + fr + ai * 128 + m * 16] : 1.0f;
;                 float v[8];
; #pragma unroll
;                 for (int n = 0; n < 2; ++n)
; #pragma unroll
;                     for (int j = 0; j < 4; ++j) { const float gt = acc[ai][0][m][n][j] * rs, up = acc[ai][1][m][n][j] * rs; v[n * 4 + j] = gt * up * __builtin_amdgcn_rcpf(1.0f + __builtin_amdgcn_exp2f(-1.4426950408889634f * gt)); }
;                 u32x4 w; w.x = pk2(v[0], v[1]); w.y = pk2(v[2], v[3]); w.z = pk2(v[4], v[5]); w.w = pk2(v[6], v[7]);
;                 *(u32x4*)(H + (size_t)(row0 + ai * 128 + m * 16) * DFF + col0) = w;
.Lxs_p1_j:
	s_barrier
	s_setprio 1
	v_mfma_f32_16x16x32_bf16 v[58:61], v[200:203], v[168:171], v[58:61]
	v_mfma_f32_16x16x32_bf16 v[50:53], v[212:215], v[168:171], v[50:53]
	v_mfma_f32_16x16x32_bf16 v[42:45], v[200:203], v[176:179], v[42:45]
	v_mfma_f32_16x16x32_bf16 v[34:37], v[212:215], v[176:179], v[34:37]
	v_mfma_f32_16x16x32_bf16 v[26:29], v[200:203], v[184:187], v[26:29]
	v_mfma_f32_16x16x32_bf16 v[18:21], v[212:215], v[184:187], v[18:21]
	v_mfma_f32_16x16x32_bf16 v[10:13], v[200:203], v[192:195], v[10:13]
	v_mfma_f32_16x16x32_bf16 v[2:5], v[212:215], v[192:195], v[2:5]
	v_mfma_f32_16x16x32_bf16 v[58:61], v[208:211], v[172:175], v[58:61]
	v_mfma_f32_16x16x32_bf16 v[50:53], v[216:219], v[172:175], v[50:53]
	v_mfma_f32_16x16x32_bf16 v[42:45], v[208:211], v[180:183], v[42:45]
	v_mfma_f32_16x16x32_bf16 v[34:37], v[216:219], v[180:183], v[34:37]
	v_mfma_f32_16x16x32_bf16 v[26:29], v[208:211], v[188:191], v[26:29]
	v_mfma_f32_16x16x32_bf16 v[18:21], v[216:219], v[188:191], v[18:21]
	v_mfma_f32_16x16x32_bf16 v[10:13], v[208:211], v[196:199], v[10:13]
	v_mfma_f32_16x16x32_bf16 v[2:5], v[216:219], v[196:199], v[2:5]
	s_setprio 0
	s_add_i32 s51, s51, 2
	s_add_u32 s22, s22, 0x100
	s_addc_u32 s23, s23, 0
	s_add_u32 s49, s49, 0x100
	s_addc_u32 s50, s50, 0
	s_cmp_gt_u32 s51, 29
	s_barrier
	s_cbranch_scc0 .LBB0_243
	v_mul_f32_e32 v153, 0xbfb8aa3b, v126
	v_exp_f32_e32 v154, v153
	v_mul_f32_e32 v153, 0xbfb8aa3b, v127
	v_pk_mul_f32 v[122:123], v[126:127], v[122:123]
	v_mul_f32_e32 v126, 0xbfb8aa3b, v128
	v_mul_f32_e32 v127, 0xbfb8aa3b, v129
	v_exp_f32_e32 v126, v126
	v_exp_f32_e32 v127, v127
	v_pk_mul_f32 v[124:125], v[128:129], v[124:125]
	v_mul_f32_e32 v129, 0xbfb8aa3b, v119
	v_add_f32_e32 v126, 1.0, v126
	v_add_f32_e32 v127, 1.0, v127
	v_rcp_f32_e32 v126, v126
	v_rcp_f32_e32 v127, v127
	v_pk_mul_f32 v[114:115], v[118:119], v[114:115]
	v_pk_mul_f32 v[106:107], v[110:111], v[106:107]
	v_pk_mul_f32 v[108:109], v[112:113], v[108:109]
	v_pk_mul_f32 v[124:125], v[126:127], v[124:125]
	v_pk_mul_f32 v[100:101], v[104:105], v[100:101]
	v_cvt_pk_bf16_f32 v119, v124, v125
	v_mul_f32_e32 v124, 0xbfb8aa3b, v110
	v_mul_f32_e32 v125, 0xbfb8aa3b, v111
	v_mul_f32_e32 v110, 0xbfb8aa3b, v112
	v_mul_f32_e32 v111, 0xbfb8aa3b, v113
	v_exp_f32_e32 v110, v110
	v_exp_f32_e32 v111, v111
	v_mul_f32_e32 v112, 0xbfb8aa3b, v102
	v_mul_f32_e32 v113, 0xbfb8aa3b, v103
	v_add_f32_e32 v110, 1.0, v110
	v_add_f32_e32 v111, 1.0, v111
	v_rcp_f32_e32 v110, v110
	v_rcp_f32_e32 v111, v111
	v_exp_f32_e32 v112, v112
	v_exp_f32_e32 v113, v113
	v_pk_mul_f32 v[90:91], v[94:95], v[90:91]
	v_pk_mul_f32 v[108:109], v[110:111], v[108:109]
	v_add_f32_e32 v110, 1.0, v112
	v_add_f32_e32 v111, 1.0, v113
	v_mul_f32_e32 v112, 0xbfb8aa3b, v104
	v_mul_f32_e32 v113, 0xbfb8aa3b, v105
	v_exp_f32_e32 v112, v112
	v_exp_f32_e32 v113, v113
	v_mul_f32_e32 v128, 0xbfb8aa3b, v118
	v_pk_mul_f32 v[92:93], v[96:97], v[92:93]
	v_add_f32_e32 v112, 1.0, v112
	v_add_f32_e32 v113, 1.0, v113
	v_rcp_f32_e32 v112, v112
	v_rcp_f32_e32 v113, v113
	v_exp_f32_e32 v128, v128
	v_exp_f32_e32 v129, v129
	v_exp_f32_e32 v155, v153
	v_pk_mul_f32 v[104:105], v[112:113], v[100:101]
	v_add_f32_e32 v126, 1.0, v128
	v_cvt_pk_bf16_f32 v101, v104, v105
	v_mul_f32_e32 v104, 0xbfb8aa3b, v94
	v_mul_f32_e32 v105, 0xbfb8aa3b, v95
	v_mul_f32_e32 v94, 0xbfb8aa3b, v96
	v_mul_f32_e32 v95, 0xbfb8aa3b, v97
	v_exp_f32_e32 v94, v94
	v_exp_f32_e32 v95, v95
	v_mul_f32_e32 v96, 0xbfb8aa3b, v86
	v_mul_f32_e32 v97, 0xbfb8aa3b, v87
	v_add_f32_e32 v94, 1.0, v94
	v_add_f32_e32 v95, 1.0, v95
	v_rcp_f32_e32 v94, v94
	v_rcp_f32_e32 v95, v95
	v_exp_f32_e32 v96, v96
	v_exp_f32_e32 v97, v97
	v_add_f32_e32 v127, 1.0, v129
	v_mul_f32_e32 v128, 0xbfb8aa3b, v120
	v_mul_f32_e32 v129, 0xbfb8aa3b, v121
	v_pk_mul_f32 v[92:93], v[94:95], v[92:93]
	v_add_f32_e32 v94, 1.0, v96
	v_add_f32_e32 v95, 1.0, v97
	v_mul_f32_e32 v96, 0xbfb8aa3b, v88
	v_mul_f32_e32 v97, 0xbfb8aa3b, v89
	v_exp_f32_e32 v128, v128
	v_exp_f32_e32 v129, v129
	v_exp_f32_e32 v96, v96
	v_exp_f32_e32 v97, v97
	v_add_f32_e32 v154, 1.0, v154
	v_add_f32_e32 v155, 1.0, v155
	v_rcp_f32_e32 v126, v126
	v_rcp_f32_e32 v127, v127
	v_add_f32_e32 v128, 1.0, v128
	v_add_f32_e32 v129, 1.0, v129
	v_add_f32_e32 v96, 1.0, v96
	v_add_f32_e32 v97, 1.0, v97
	v_rcp_f32_e32 v154, v154
	v_rcp_f32_e32 v155, v155
	v_rcp_f32_e32 v128, v128
	v_rcp_f32_e32 v129, v129
	v_rcp_f32_e32 v96, v96
	v_rcp_f32_e32 v97, v97
	v_lshl_or_b32 v152, s46, 7, v147
	v_pk_mul_f32 v[116:117], v[120:121], v[116:117]
	v_pk_mul_f32 v[114:115], v[126:127], v[114:115]
	v_exp_f32_e32 v124, v124
	v_exp_f32_e32 v125, v125
	v_pk_mul_f32 v[84:85], v[88:89], v[84:85]
	v_lshl_add_u32 v151, s20, 8, v1
	v_ashrrev_i32_e32 v153, 31, v152
	v_pk_mul_f32 v[122:123], v[154:155], v[122:123]
	v_pk_mul_f32 v[116:117], v[128:129], v[116:117]
	v_cvt_pk_bf16_f32 v120, v114, v115
	v_mov_b64_e32 v[114:115], s[2:3]
	v_pk_mul_f32 v[88:89], v[96:97], v[84:85]
	v_cvt_pk_bf16_f32 v118, v122, v123
	v_cvt_pk_bf16_f32 v121, v116, v117
	v_mad_i64_i32 v[122:123], s[22:23], v151, s45, v[114:115]
	v_lshlrev_b64 v[116:117], 1, v[152:153]
	v_cvt_pk_bf16_f32 v85, v88, v89
	v_mul_f32_e32 v88, 0xbfb8aa3b, v78
	v_mul_f32_e32 v89, 0xbfb8aa3b, v79
	v_pk_mul_f32 v[74:75], v[78:79], v[74:75]
	v_mul_f32_e32 v78, 0xbfb8aa3b, v80
	v_mul_f32_e32 v79, 0xbfb8aa3b, v81
	v_lshl_add_u64 v[122:123], v[122:123], 0, v[116:117]
	v_rcp_f32_e32 v110, v110
	v_rcp_f32_e32 v111, v111
	v_exp_f32_e32 v78, v78
	v_exp_f32_e32 v79, v79
	global_store_dwordx4 v[122:123], v[118:121], off
	v_pk_mul_f32 v[98:99], v[102:103], v[98:99]
	v_exp_f32_e32 v104, v104
	v_add_f32_e32 v118, 1.0, v124
	v_add_f32_e32 v119, 1.0, v125
	v_rcp_f32_e32 v118, v118
; #define LAS __attribute__((address_space(3)))
; DI unsigned pk2(float a, float b) { f32x2_t v = {a, b}; return __builtin_bit_cast(unsigned, __builtin_convertvector(v, bf16x2_t)); }
;     DI void operator()(const f32x4 (&acc)[2][2][4][2], const pg8::Unit& u, int wr, int wc, int fr, int fq, int ui, LAS unsigned char* lds) const {
;         const int row0 = u.pm * 256 + wr * 64 + fr, col0 = u.pn * 128 + wc * 32 + 8 * fq;
; #pragma unroll
;         for (int ai = 0; ai < 2; ++ai)
; #pragma unroll
;             for (int m = 0; m < 4; ++m) {
;                 const float rs = ss ? ((const LAS float*)(lds + 131072))[ui * 256 + wr * 64 + fr + ai * 128 + m * 16] : 1.0f;
;                 float v[8];
; #pragma unroll
;                 for (int n = 0; n < 2; ++n)
; #pragma unroll
;                     for (int j = 0; j < 4; ++j) { const float gt = acc[ai][0][m][n][j] * rs, up = acc[ai][1][m][n][j] * rs; v[n * 4 + j] = gt * up * __builtin_amdgcn_rcpf(1.0f + __builtin_amdgcn_exp2f(-1.4426950408889634f * gt)); }
;                 u32x4 w; w.x = pk2(v[0], v[1]); w.y = pk2(v[2], v[3]); w.z = pk2(v[4], v[5]); w.w = pk2(v[6], v[7]);
;                 *(u32x4*)(H + (size_t)(row0 + ai * 128 + m * 16) * DFF + col0) = w;
	v_rcp_f32_e32 v119, v119
	v_pk_mul_f32 v[102:103], v[110:111], v[98:99]
	v_exp_f32_e32 v105, v105
	v_pk_mul_f32 v[76:77], v[80:81], v[76:77]
	v_add_f32_e32 v78, 1.0, v78
	v_add_f32_e32 v79, 1.0, v79
	v_mul_f32_e32 v80, 0xbfb8aa3b, v70
	v_mul_f32_e32 v81, 0xbfb8aa3b, v71
	v_cvt_pk_bf16_f32 v100, v102, v103
	v_or_b32_e32 v102, 16, v151
	v_rcp_f32_e32 v78, v78
	v_rcp_f32_e32 v79, v79
	v_exp_f32_e32 v80, v80
	v_exp_f32_e32 v81, v81
	v_pk_mul_f32 v[106:107], v[118:119], v[106:107]
	v_mad_i64_i32 v[102:103], s[22:23], v102, s45, v[114:115]
	v_cvt_pk_bf16_f32 v98, v106, v107
	v_cvt_pk_bf16_f32 v99, v108, v109
	v_lshl_add_u64 v[102:103], v[102:103], 0, v[116:117]
	v_rcp_f32_e32 v94, v94
	v_rcp_f32_e32 v95, v95
	global_store_dwordx4 v[102:103], v[98:101], off
	v_pk_mul_f32 v[76:77], v[78:79], v[76:77]
	v_add_f32_e32 v78, 1.0, v80
	v_add_f32_e32 v98, 1.0, v104
	v_add_f32_e32 v99, 1.0, v105
	v_rcp_f32_e32 v98, v98
	v_rcp_f32_e32 v99, v99
	v_add_f32_e32 v79, 1.0, v81
	v_mul_f32_e32 v80, 0xbfb8aa3b, v72
	v_mul_f32_e32 v81, 0xbfb8aa3b, v73
	v_pk_mul_f32 v[82:83], v[86:87], v[82:83]
	v_exp_f32_e32 v80, v80
	v_exp_f32_e32 v81, v81
	v_pk_mul_f32 v[86:87], v[94:95], v[82:83]
	v_exp_f32_e32 v88, v88
	v_exp_f32_e32 v89, v89
	v_cvt_pk_bf16_f32 v84, v86, v87
	v_or_b32_e32 v86, 32, v151
	v_pk_mul_f32 v[90:91], v[98:99], v[90:91]
	v_mad_i64_i32 v[86:87], s[22:23], v86, s45, v[114:115]
	v_cvt_pk_bf16_f32 v82, v90, v91
	v_cvt_pk_bf16_f32 v83, v92, v93
	v_lshl_add_u64 v[86:87], v[86:87], 0, v[116:117]
	v_rcp_f32_e32 v78, v78
	v_rcp_f32_e32 v79, v79
	v_add_f32_e32 v80, 1.0, v80
	v_add_f32_e32 v81, 1.0, v81
	global_store_dwordx4 v[86:87], v[82:85], off
	v_rcp_f32_e32 v80, v80
	v_rcp_f32_e32 v81, v81
	v_add_f32_e32 v82, 1.0, v88
	v_add_f32_e32 v83, 1.0, v89
	v_rcp_f32_e32 v82, v82
	v_rcp_f32_e32 v83, v83
	v_pk_mul_f32 v[66:67], v[70:71], v[66:67]
	v_pk_mul_f32 v[68:69], v[72:73], v[68:69]
	v_pk_mul_f32 v[70:71], v[78:79], v[66:67]
	v_pk_mul_f32 v[72:73], v[80:81], v[68:69]
	v_cvt_pk_bf16_f32 v68, v70, v71
	v_or_b32_e32 v70, 48, v151
	v_pk_mul_f32 v[74:75], v[82:83], v[74:75]
	v_mad_i64_i32 v[70:71], s[22:23], v70, s45, v[114:115]
	v_cvt_pk_bf16_f32 v66, v74, v75
	v_cvt_pk_bf16_f32 v67, v76, v77
	v_cvt_pk_bf16_f32 v69, v72, v73
	v_lshl_add_u64 v[70:71], v[70:71], 0, v[116:117]
	global_store_dwordx4 v[70:71], v[66:69], off
	v_pk_mul_f32 v[58:59], v[62:63], v[58:59]
	v_pk_mul_f32 v[60:61], v[64:65], v[60:61]
	v_mul_f32_e32 v66, 0xbfb8aa3b, v62
	v_mul_f32_e32 v67, 0xbfb8aa3b, v63
	v_mul_f32_e32 v62, 0xbfb8aa3b, v64
	v_mul_f32_e32 v63, 0xbfb8aa3b, v65
	v_exp_f32_e32 v62, v62
	v_exp_f32_e32 v63, v63
	v_mul_f32_e32 v64, 0xbfb8aa3b, v54
	v_mul_f32_e32 v65, 0xbfb8aa3b, v55
	v_add_f32_e32 v62, 1.0, v62
	v_add_f32_e32 v63, 1.0, v63
	v_rcp_f32_e32 v62, v62
	v_rcp_f32_e32 v63, v63
	v_exp_f32_e32 v64, v64
	v_exp_f32_e32 v65, v65
	v_pk_mul_f32 v[52:53], v[56:57], v[52:53]
	v_pk_mul_f32 v[60:61], v[62:63], v[60:61]
	v_add_f32_e32 v62, 1.0, v64
	v_add_f32_e32 v63, 1.0, v65
	v_mul_f32_e32 v64, 0xbfb8aa3b, v56
	v_mul_f32_e32 v65, 0xbfb8aa3b, v57
	v_exp_f32_e32 v64, v64
	v_exp_f32_e32 v65, v65
	v_pk_mul_f32 v[42:43], v[46:47], v[42:43]
	v_pk_mul_f32 v[44:45], v[48:49], v[44:45]
	v_add_f32_e32 v64, 1.0, v64
	v_add_f32_e32 v65, 1.0, v65
	v_rcp_f32_e32 v64, v64
	v_rcp_f32_e32 v65, v65
	v_pk_mul_f32 v[36:37], v[40:41], v[36:37]
	v_pk_mul_f32 v[26:27], v[30:31], v[26:27]
	v_pk_mul_f32 v[28:29], v[32:33], v[28:29]
	v_pk_mul_f32 v[56:57], v[64:65], v[52:53]
	v_exp_f32_e32 v66, v66
	v_cvt_pk_bf16_f32 v53, v56, v57
	v_mul_f32_e32 v56, 0xbfb8aa3b, v46
	v_mul_f32_e32 v57, 0xbfb8aa3b, v47
	v_mul_f32_e32 v46, 0xbfb8aa3b, v48
	v_mul_f32_e32 v47, 0xbfb8aa3b, v49
	v_exp_f32_e32 v46, v46
	v_exp_f32_e32 v47, v47
	v_mul_f32_e32 v48, 0xbfb8aa3b, v38
	v_mul_f32_e32 v49, 0xbfb8aa3b, v39
	v_add_f32_e32 v46, 1.0, v46
	v_add_f32_e32 v47, 1.0, v47
	v_rcp_f32_e32 v46, v46
	v_rcp_f32_e32 v47, v47
	v_exp_f32_e32 v48, v48
	v_exp_f32_e32 v49, v49
	v_exp_f32_e32 v67, v67
	v_pk_mul_f32 v[44:45], v[46:47], v[44:45]
	v_add_f32_e32 v46, 1.0, v48
	v_add_f32_e32 v47, 1.0, v49
	v_mul_f32_e32 v48, 0xbfb8aa3b, v40
	v_mul_f32_e32 v49, 0xbfb8aa3b, v41
	v_exp_f32_e32 v48, v48
	v_exp_f32_e32 v49, v49
	v_add_f32_e32 v66, 1.0, v66
	v_add_f32_e32 v67, 1.0, v67
	v_add_f32_e32 v48, 1.0, v48
	v_add_f32_e32 v49, 1.0, v49
	v_rcp_f32_e32 v48, v48
	v_rcp_f32_e32 v49, v49
	v_rcp_f32_e32 v62, v62
	v_rcp_f32_e32 v63, v63
	v_rcp_f32_e32 v66, v66
	v_pk_mul_f32 v[40:41], v[48:49], v[36:37]
	v_rcp_f32_e32 v67, v67
	v_cvt_pk_bf16_f32 v37, v40, v41
; #define LAS __attribute__((address_space(3)))
; DI unsigned pk2(float a, float b) { f32x2_t v = {a, b}; return __builtin_bit_cast(unsigned, __builtin_convertvector(v, bf16x2_t)); }
; #define PG8_WAIT_V(n) asm volatile("s_waitcnt vmcnt(" #n ")" ::: "memory")
; #define PG8_BAR __builtin_amdgcn_s_barrier()
; template <class Epi, class Sched>
; __device__ __forceinline__ void gemm_phase(LAS unsigned char* lds, const Gemm g, const Sched& S, const Epi& E) {
;     ...
;         E(acc, cur, wr, wc, fr, fq, ui, lds); S.done(cur);
;         if (!has_next) break;
; #pragma unroll
;         for (int a = 0; a < 2; ++a)
; #pragma unroll
;             for (int b = 0; b < 2; ++b)
; #pragma unroll
;                 for (int m = 0; m < 4; ++m)
; #pragma unroll
;                     for (int n = 0; n < 2; ++n) acc[a][b][m][n] = (f32x4){0.f, 0.f, 0.f, 0.f};
;         cur = nxt; cA = nA; cB = nB; ++ui;
;     }
;     PG8_WAIT_V(0);
;     if (wr == 0) PG8_BAR;
;     PG8_BAR;
;     DI void operator()(const f32x4 (&acc)[2][2][4][2], const pg8::Unit& u, int wr, int wc, int fr, int fq, int ui, LAS unsigned char* lds) const {
;     ...
;             for (int m = 0; m < 4; ++m) {
;                 const float rs = ss ? ((const LAS float*)(lds + 131072))[ui * 256 + wr * 64 + fr + ai * 128 + m * 16] : 1.0f;
;                 float v[8];
; #pragma unroll
;                 for (int n = 0; n < 2; ++n)
; #pragma unroll
;                     for (int j = 0; j < 4; ++j) { const float gt = acc[ai][0][m][n][j] * rs, up = acc[ai][1][m][n][j] * rs; v[n * 4 + j] = gt * up * __builtin_amdgcn_rcpf(1.0f + __builtin_amdgcn_exp2f(-1.4426950408889634f * gt)); }
;                 u32x4 w; w.x = pk2(v[0], v[1]); w.y = pk2(v[2], v[3]); w.z = pk2(v[4], v[5]); w.w = pk2(v[6], v[7]);
;                 *(u32x4*)(H + (size_t)(row0 + ai * 128 + m * 16) * DFF + col0) = w;
	v_mul_f32_e32 v40, 0xbfb8aa3b, v30
	v_mul_f32_e32 v41, 0xbfb8aa3b, v31
	v_mul_f32_e32 v30, 0xbfb8aa3b, v32
	v_mul_f32_e32 v31, 0xbfb8aa3b, v33
	v_exp_f32_e32 v30, v30
	v_exp_f32_e32 v31, v31
	v_mul_f32_e32 v32, 0xbfb8aa3b, v22
	v_mul_f32_e32 v33, 0xbfb8aa3b, v23
	v_add_f32_e32 v30, 1.0, v30
	v_add_f32_e32 v31, 1.0, v31
	v_rcp_f32_e32 v30, v30
	v_rcp_f32_e32 v31, v31
	v_exp_f32_e32 v32, v32
	v_exp_f32_e32 v33, v33
	v_pk_mul_f32 v[50:51], v[54:55], v[50:51]
	v_pk_mul_f32 v[28:29], v[30:31], v[28:29]
	v_add_f32_e32 v30, 1.0, v32
	v_add_f32_e32 v31, 1.0, v33
	v_mul_f32_e32 v32, 0xbfb8aa3b, v24
	v_mul_f32_e32 v33, 0xbfb8aa3b, v25
	v_exp_f32_e32 v32, v32
	v_exp_f32_e32 v33, v33
	v_exp_f32_e32 v56, v56
	v_exp_f32_e32 v57, v57
	v_add_f32_e32 v32, 1.0, v32
	v_add_f32_e32 v33, 1.0, v33
	v_rcp_f32_e32 v32, v32
	v_rcp_f32_e32 v33, v33
	v_pk_mul_f32 v[20:21], v[24:25], v[20:21]
	v_add_u32_e32 v68, 0x80, v151
	v_pk_mul_f32 v[54:55], v[62:63], v[50:51]
	v_pk_mul_f32 v[24:25], v[32:33], v[20:21]
	v_pk_mul_f32 v[58:59], v[66:67], v[58:59]
	v_cvt_pk_bf16_f32 v52, v54, v55
	v_mad_i64_i32 v[54:55], s[22:23], v68, s45, v[114:115]
	v_cvt_pk_bf16_f32 v21, v24, v25
	v_mul_f32_e32 v24, 0xbfb8aa3b, v14
	v_mul_f32_e32 v25, 0xbfb8aa3b, v15
	v_pk_mul_f32 v[10:11], v[14:15], v[10:11]
	v_mul_f32_e32 v14, 0xbfb8aa3b, v16
	v_mul_f32_e32 v15, 0xbfb8aa3b, v17
	v_cvt_pk_bf16_f32 v50, v58, v59
	v_cvt_pk_bf16_f32 v51, v60, v61
	v_lshl_add_u64 v[54:55], v[54:55], 0, v[116:117]
	v_rcp_f32_e32 v46, v46
	v_rcp_f32_e32 v47, v47
	v_exp_f32_e32 v14, v14
	v_exp_f32_e32 v15, v15
	global_store_dwordx4 v[54:55], v[50:53], off
	v_pk_mul_f32 v[34:35], v[38:39], v[34:35]
	v_exp_f32_e32 v40, v40
	v_add_f32_e32 v50, 1.0, v56
	v_add_f32_e32 v51, 1.0, v57
	v_rcp_f32_e32 v50, v50
	v_rcp_f32_e32 v51, v51
	v_pk_mul_f32 v[38:39], v[46:47], v[34:35]
	v_exp_f32_e32 v41, v41
	v_pk_mul_f32 v[12:13], v[16:17], v[12:13]
	v_add_f32_e32 v14, 1.0, v14
	v_add_f32_e32 v15, 1.0, v15
	v_mul_f32_e32 v16, 0xbfb8aa3b, v6
	v_mul_f32_e32 v17, 0xbfb8aa3b, v7
	v_cvt_pk_bf16_f32 v36, v38, v39
	v_add_u32_e32 v38, 0x90, v151
	v_rcp_f32_e32 v14, v14
	v_rcp_f32_e32 v15, v15
	v_exp_f32_e32 v16, v16
	v_exp_f32_e32 v17, v17
	v_pk_mul_f32 v[42:43], v[50:51], v[42:43]
	v_mad_i64_i32 v[38:39], s[22:23], v38, s45, v[114:115]
	v_cvt_pk_bf16_f32 v34, v42, v43
	v_cvt_pk_bf16_f32 v35, v44, v45
	v_lshl_add_u64 v[38:39], v[38:39], 0, v[116:117]
	v_rcp_f32_e32 v30, v30
	v_rcp_f32_e32 v31, v31
	global_store_dwordx4 v[38:39], v[34:37], off
	v_pk_mul_f32 v[12:13], v[14:15], v[12:13]
	v_add_f32_e32 v14, 1.0, v16
	v_add_f32_e32 v34, 1.0, v40
	v_add_f32_e32 v35, 1.0, v41
	v_rcp_f32_e32 v34, v34
	v_rcp_f32_e32 v35, v35
	v_add_f32_e32 v15, 1.0, v17
	v_mul_f32_e32 v16, 0xbfb8aa3b, v8
	v_mul_f32_e32 v17, 0xbfb8aa3b, v9
	v_pk_mul_f32 v[18:19], v[22:23], v[18:19]
	v_exp_f32_e32 v16, v16
	v_exp_f32_e32 v17, v17
	v_pk_mul_f32 v[22:23], v[30:31], v[18:19]
	v_exp_f32_e32 v24, v24
	v_exp_f32_e32 v25, v25
	v_cvt_pk_bf16_f32 v20, v22, v23
	v_add_u32_e32 v22, 0xa0, v151
	v_pk_mul_f32 v[26:27], v[34:35], v[26:27]
	v_mad_i64_i32 v[22:23], s[22:23], v22, s45, v[114:115]
	v_cvt_pk_bf16_f32 v18, v26, v27
	v_cvt_pk_bf16_f32 v19, v28, v29
	v_lshl_add_u64 v[22:23], v[22:23], 0, v[116:117]
	v_rcp_f32_e32 v14, v14
	v_rcp_f32_e32 v15, v15
	v_add_f32_e32 v16, 1.0, v16
	v_add_f32_e32 v17, 1.0, v17
	global_store_dwordx4 v[22:23], v[18:21], off
	v_rcp_f32_e32 v16, v16
	v_rcp_f32_e32 v17, v17
	v_add_f32_e32 v18, 1.0, v24
	v_add_f32_e32 v19, 1.0, v25
	v_rcp_f32_e32 v18, v18
	v_rcp_f32_e32 v19, v19
	v_pk_mul_f32 v[2:3], v[6:7], v[2:3]
	v_pk_mul_f32 v[4:5], v[8:9], v[4:5]
	v_pk_mul_f32 v[6:7], v[14:15], v[2:3]
	v_pk_mul_f32 v[8:9], v[16:17], v[4:5]
	v_cvt_pk_bf16_f32 v4, v6, v7
	v_add_u32_e32 v6, 0xb0, v151
	v_pk_mul_f32 v[10:11], v[18:19], v[10:11]
	v_mad_i64_i32 v[6:7], s[22:23], v6, s45, v[114:115]
	v_readlane_b32 s48, v245, 5
	v_cvt_pk_bf16_f32 v2, v10, v11
	v_cvt_pk_bf16_f32 v3, v12, v13
	v_cvt_pk_bf16_f32 v5, v8, v9
	v_lshl_add_u64 v[6:7], v[6:7], 0, v[116:117]
	s_and_b64 vcc, exec, s[4:5]
	s_mov_b32 s46, s8
	s_mov_b32 s20, s14
	s_mov_b64 s[24:25], s[18:19]
	s_mov_b64 s[22:23], s[16:17]
	v_readlane_b32 s49, v245, 6
	v_readlane_b32 s50, v245, 7
	v_readlane_b32 s51, v245, 8
	v_readlane_b32 s52, v245, 9
	v_readlane_b32 s53, v245, 10
	v_readlane_b32 s54, v245, 11
	v_readlane_b32 s55, v245, 12
	global_store_dwordx4 v[6:7], v[2:5], off
	s_cbranch_vccz .LBB0_240
	s_waitcnt vmcnt(0)
	s_cmpk_gt_u32 s28, 0xff
	s_cbranch_scc1 .LBB0_247
	s_barrier

; #define PG8_STAGE(bufoff, gbase, voff) do { _Pragma("unroll") for (int _i = 0; _i < 2; ++_i) \
;         __builtin_amdgcn_global_load_lds((const unsigned*)((const char*)(gbase) + (voff)[_i]), (LAS unsigned*)(lds + (bufoff) + ldsw + _i * 8192), 16, 0, 0); } while (0)
; #define PG8_LDA(dst, b, h) do { _Pragma("unroll") for (int m = 0; m < 4; ++m) _Pragma("unroll") for (int k = 0; k < 2; ++k) dst[m][k] = *(const LAS bf16x8*)(lds + PG8_SA(b, h) + aoff + m * 2048 + k * 1024); } while (0)
; #define PG8_LDB(dst, b, h) do { _Pragma("unroll") for (int n = 0; n < 2; ++n) _Pragma("unroll") for (int k = 0; k < 2; ++k) dst[n][k] = *(const LAS bf16x8*)(lds + PG8_SB(b, h) + boff + n * 2048 + k * 1024); } while (0)
; #define PG8_WAIT_L(n) asm volatile("s_waitcnt lgkmcnt(" #n ")" ::: "memory")
; #define PG8_BAR __builtin_amdgcn_s_barrier()
; #define PG8_SCHED __builtin_amdgcn_sched_barrier(0)
; template <class Epi, class Sched>
; __device__ __forceinline__ void gemm_phase(LAS unsigned char* lds, const Gemm g, const Sched& S, const Epi& E) {
;     ...
;         const bool has_next = S.next(ui + 1, nxt);
;         const char* nA = has_next ? (const char*)g.A + (size_t)nxt.pm * tstep : cA; const char* nB = has_next ? (const char*)g.Bt + (size_t)nxt.pn * tstep : cB;
;         for (int t = 0; t < nt; t += 2) {
;             const bool last = (t == nt - 2);
;             const char* a1 = cA + (size_t)(t + 1) * kstep;
;             const char* a2 = last ? nA : cA + (size_t)(t + 2) * kstep; const char* b2 = last ? nB : cB + (size_t)(t + 2) * kstep;
;             const char* a3 = a2 + kstep; const char* b3 = b2 + kstep;
;             if (last && has_next) S.a_ready(nxt);
;             PG8_LDB(B0, 0, 0); PG8_SCHED; PG8_LDA(At, 0, 0); PG8_STAGE(PG8_SA(1, 1), a1 + hstep, voffA);
;             PG8_WAIT_L(8); PG8_BAR; PG8_WAIT_L(0); PG8_MMA(0, 0, At, B0); PG8_BAR; PG8_SCHED;
;             PG8_LDB(B1, 0, 1); PG8_STAGE(PG8_SB(0, 0), b2, voffB);
;             PG8_BAR; PG8_WAIT_L(0); PG8_MMA(0, 1, At, B1); PG8_BAR;
;             PG8_LDA(At, 0, 1); PG8_STAGE(PG8_SA(0, 0), a2, voffA);
;             PG8_BAR; PG8_WAIT_L(0); PG8_MMA(1, 0, At, B0); PG8_BAR; PG8_SCHED;
;             PG8_STAGE(PG8_SB(0, 1), b2 + hstep, voffB);
.LBB0_1090:
	s_ashr_i32 s11, s10, 31
	v_cmp_lt_i64_e32 vcc, s[12:13], v[142:143]
	s_lshl_b64 s[12:13], s[10:11], 20
	s_add_u32 s12, s28, s12
	s_addc_u32 s13, s29, s13
	s_and_b64 s[14:15], vcc, exec
	s_cselect_b32 s11, s13, s19
	s_cselect_b32 s45, s12, s18
	s_ashr_i32 s9, s8, 31
	s_lshl_b64 s[14:15], s[8:9], 20
	s_add_u32 s14, s30, s14
	s_addc_u32 s15, s31, s15
	s_and_b64 s[22:23], vcc, exec
	s_cselect_b32 s9, s15, s21
	s_cselect_b32 s46, s14, s20
	s_add_u32 s18, s18, 0x80080
	s_addc_u32 s19, s19, 0
	s_add_u32 s47, s20, 0x100
	s_addc_u32 s48, s21, 0
	s_mov_b32 s49, -2
	ds_read_b128 v[152:155], v149
	ds_read_b128 v[156:159], v149 offset:1024
	ds_read_b128 v[160:163], v149 offset:2048
	ds_read_b128 v[164:167], v149 offset:3072
	s_add_u32 s20, s18, 0xfff80080
	s_addc_u32 s21, s19, -1
	s_cmp_eq_u32 s49, 28
	s_cselect_b32 s23, s11, s21
	s_cselect_b32 s22, s45, s20
	s_cselect_b32 s21, s9, s48
	s_cselect_b32 s20, s46, s47
	v_lshl_add_u64 v[200:201], s[18:19], 0, v[138:139]
	s_add_i32 m0, s17, 0xc000
	ds_read_b128 v[168:171], v150
	ds_read_b128 v[172:175], v150 offset:1024
	ds_read_b128 v[176:179], v150 offset:2048
	ds_read_b128 v[180:183], v150 offset:3072
	ds_read_b128 v[184:187], v150 offset:4096
	ds_read_b128 v[188:191], v150 offset:5120
	ds_read_b128 v[192:195], v150 offset:6144
	ds_read_b128 v[196:199], v150 offset:7168
	s_cmp_eq_u32 s43, 0
	s_cbranch_scc0 .Lps_p10_skip
	global_load_lds_dwordx4 v[200:201], off
	v_lshl_add_u64 v[200:201], s[18:19], 0, v[140:141]
	s_add_i32 m0, s17, 0xe000
	s_nop 0
	global_load_lds_dwordx4 v[200:201], off
.Lps_p10_skip:
	s_waitcnt lgkmcnt(8)
	s_barrier
	s_waitcnt lgkmcnt(0)
	s_setprio 1
	s_waitcnt lgkmcnt(0)
	v_mfma_f32_16x16x32_bf16 v[126:129], v[152:155], v[168:171], 0
	v_mfma_f32_16x16x32_bf16 v[122:125], v[160:163], v[168:171], 0
	v_mfma_f32_16x16x32_bf16 v[110:113], v[152:155], v[176:179], 0
	v_mfma_f32_16x16x32_bf16 v[106:109], v[160:163], v[176:179], 0
	v_mfma_f32_16x16x32_bf16 v[94:97], v[152:155], v[184:187], 0
	v_mfma_f32_16x16x32_bf16 v[90:93], v[160:163], v[184:187], 0
	v_mfma_f32_16x16x32_bf16 v[78:81], v[152:155], v[192:195], 0
	v_mfma_f32_16x16x32_bf16 v[74:77], v[160:163], v[192:195], 0
	v_mfma_f32_16x16x32_bf16 v[126:129], v[156:159], v[172:175], v[126:129]
	v_mfma_f32_16x16x32_bf16 v[122:125], v[164:167], v[172:175], v[122:125]
	v_mfma_f32_16x16x32_bf16 v[110:113], v[156:159], v[180:183], v[110:113]
	v_mfma_f32_16x16x32_bf16 v[106:109], v[164:167], v[180:183], v[106:109]
	v_mfma_f32_16x16x32_bf16 v[94:97], v[156:159], v[188:191], v[94:97]
	v_mfma_f32_16x16x32_bf16 v[90:93], v[164:167], v[188:191], v[90:93]
	v_mfma_f32_16x16x32_bf16 v[78:81], v[156:159], v[196:199], v[78:81]
	v_mfma_f32_16x16x32_bf16 v[74:77], v[164:167], v[196:199], v[74:77]
	s_setprio 0
	s_barrier
	s_add_i32 s50, s39, s27
	v_lshl_add_u64 v[204:205], s[20:21], 0, v[132:133]
	s_mov_b32 m0, s50
	ds_read_b128 v[200:203], v151
	ds_read_b128 v[208:211], v151 offset:1024
	ds_read_b128 v[212:215], v151 offset:2048
	ds_read_b128 v[216:219], v151 offset:3072
	global_load_lds_dwordx4 v[204:205], off
	v_lshl_add_u64 v[220:221], s[20:21], 0, v[136:137]
	s_add_i32 m0, s50, 0x2000
	s_nop 0
	global_load_lds_dwordx4 v[220:221], off
	s_barrier
	s_waitcnt lgkmcnt(0)
	s_setprio 1
	s_waitcnt lgkmcnt(0)
	v_mfma_f32_16x16x32_bf16 v[118:121], v[200:203], v[168:171], 0
	v_mfma_f32_16x16x32_bf16 v[114:117], v[212:215], v[168:171], 0
	v_mfma_f32_16x16x32_bf16 v[102:105], v[200:203], v[176:179], 0
	v_mfma_f32_16x16x32_bf16 v[98:101], v[212:215], v[176:179], 0
	v_mfma_f32_16x16x32_bf16 v[86:89], v[200:203], v[184:187], 0
	v_mfma_f32_16x16x32_bf16 v[82:85], v[212:215], v[184:187], 0
	v_mfma_f32_16x16x32_bf16 v[70:73], v[200:203], v[192:195], 0
	v_mfma_f32_16x16x32_bf16 v[66:69], v[212:215], v[192:195], 0
	v_mfma_f32_16x16x32_bf16 v[118:121], v[208:211], v[172:175], v[118:121]
	v_mfma_f32_16x16x32_bf16 v[114:117], v[216:219], v[172:175], v[114:117]
	v_mfma_f32_16x16x32_bf16 v[102:105], v[208:211], v[180:183], v[102:105]
	v_mfma_f32_16x16x32_bf16 v[98:101], v[216:219], v[180:183], v[98:101]
	v_mfma_f32_16x16x32_bf16 v[86:89], v[208:211], v[188:191], v[86:89]
	v_mfma_f32_16x16x32_bf16 v[82:85], v[216:219], v[188:191], v[82:85]
	v_mfma_f32_16x16x32_bf16 v[70:73], v[208:211], v[196:199], v[70:73]
	v_mfma_f32_16x16x32_bf16 v[66:69], v[216:219], v[196:199], v[66:69]
	s_setprio 0
	s_mov_b32 m0, s17
	v_lshl_add_u64 v[222:223], s[22:23], 0, v[130:131]
	s_barrier
	ds_read_b128 v[168:171], v150 offset:16384
	ds_read_b128 v[172:175], v150 offset:17408
	ds_read_b128 v[176:179], v150 offset:18432
	ds_read_b128 v[180:183], v150 offset:19456
	ds_read_b128 v[184:187], v150 offset:20480
	ds_read_b128 v[188:191], v150 offset:21504
	ds_read_b128 v[192:195], v150 offset:22528
	ds_read_b128 v[196:199], v150 offset:23552
	global_load_lds_dwordx4 v[222:223], off
	v_lshl_add_u64 v[224:225], s[22:23], 0, v[134:135]
	s_mov_b32 m0, s34
	s_nop 0
	global_load_lds_dwordx4 v[224:225], off
	s_barrier
	s_waitcnt lgkmcnt(0)
	s_setprio 1
	s_waitcnt lgkmcnt(0)
	v_mfma_f32_16x16x32_bf16 v[62:65], v[152:155], v[168:171], 0
	v_mfma_f32_16x16x32_bf16 v[58:61], v[160:163], v[168:171], 0
	v_mfma_f32_16x16x32_bf16 v[46:49], v[152:155], v[176:179], 0
	v_mfma_f32_16x16x32_bf16 v[42:45], v[160:163], v[176:179], 0
	v_mfma_f32_16x16x32_bf16 v[30:33], v[152:155], v[184:187], 0
	v_mfma_f32_16x16x32_bf16 v[26:29], v[160:163], v[184:187], 0
	v_mfma_f32_16x16x32_bf16 v[14:17], v[152:155], v[192:195], 0
	v_mfma_f32_16x16x32_bf16 v[10:13], v[160:163], v[192:195], 0
	v_mfma_f32_16x16x32_bf16 v[62:65], v[156:159], v[172:175], v[62:65]
	v_mfma_f32_16x16x32_bf16 v[58:61], v[164:167], v[172:175], v[58:61]
	v_mfma_f32_16x16x32_bf16 v[46:49], v[156:159], v[180:183], v[46:49]
	v_mfma_f32_16x16x32_bf16 v[42:45], v[164:167], v[180:183], v[42:45]
	v_mfma_f32_16x16x32_bf16 v[30:33], v[156:159], v[188:191], v[30:33]
	v_mfma_f32_16x16x32_bf16 v[26:29], v[164:167], v[188:191], v[26:29]
	v_mfma_f32_16x16x32_bf16 v[14:17], v[156:159], v[196:199], v[14:17]
	v_mfma_f32_16x16x32_bf16 v[10:13], v[164:167], v[196:199], v[10:13]
	s_setprio 0
	s_barrier
	s_add_u32 s50, s20, 0x80000
	s_addc_u32 s51, s21, 0
	s_add_i32 s52, s40, s27
	v_lshl_add_u64 v[152:153], s[50:51], 0, v[132:133]
	s_mov_b32 m0, s52
	s_nop 0
	global_load_lds_dwordx4 v[152:153], off
	v_lshl_add_u64 v[152:153], s[50:51], 0, v[136:137]
	s_add_i32 m0, s52, 0x2000
	s_nop 0
	global_load_lds_dwordx4 v[152:153], off
	s_cmp_eq_u32 s43, 0
	s_cbranch_scc1 .Lpw_p10_strict
	s_waitcnt vmcnt(14)
	s_branch .Lpw_p10_go

; #define PG8_STAGE(bufoff, gbase, voff) do { _Pragma("unroll") for (int _i = 0; _i < 2; ++_i) \
;         __builtin_amdgcn_global_load_lds((const unsigned*)((const char*)(gbase) + (voff)[_i]), (LAS unsigned*)(lds + (bufoff) + ldsw + _i * 8192), 16, 0, 0); } while (0)
; #define PG8_LDA(dst, b, h) do { _Pragma("unroll") for (int m = 0; m < 4; ++m) _Pragma("unroll") for (int k = 0; k < 2; ++k) dst[m][k] = *(const LAS bf16x8*)(lds + PG8_SA(b, h) + aoff + m * 2048 + k * 1024); } while (0)
; #define PG8_LDB(dst, b, h) do { _Pragma("unroll") for (int n = 0; n < 2; ++n) _Pragma("unroll") for (int k = 0; k < 2; ++k) dst[n][k] = *(const LAS bf16x8*)(lds + PG8_SB(b, h) + boff + n * 2048 + k * 1024); } while (0)
; #define PG8_MMA(ai, bj, At, Bt) do { __builtin_amdgcn_s_setprio(1); _Pragma("unroll") for (int m = 0; m < 4; ++m) _Pragma("unroll") for (int n = 0; n < 2; ++n) _Pragma("unroll") for (int k = 0; k < 2; ++k) \
;         acc[ai][bj][m][n] = __builtin_amdgcn_mfma_f32_16x16x32_bf16(Bt[n][k], At[m][k], acc[ai][bj][m][n], 0, 0, 0); __builtin_amdgcn_s_setprio(0); } while (0)
; #define PG8_WAIT_V(n) asm volatile("s_waitcnt vmcnt(" #n ")" ::: "memory")
; #define PG8_WAIT_L(n) asm volatile("s_waitcnt lgkmcnt(" #n ")" ::: "memory")
; #define PG8_BAR __builtin_amdgcn_s_barrier()
; #define PG8_SCHED __builtin_amdgcn_sched_barrier(0)
; template <class Epi, class Sched>
; __device__ __forceinline__ void gemm_phase(LAS unsigned char* lds, const Gemm g, const Sched& S, const Epi& E) {
;     ...
;             PG8_WAIT_V(6); PG8_BAR; PG8_MMA(1, 1, At, B1); PG8_BAR;
;             PG8_LDB(B0, 1, 0); PG8_SCHED; PG8_LDA(At, 1, 0); PG8_STAGE(PG8_SA(0, 1), a2 + hstep, voffA);
;             PG8_WAIT_L(8); PG8_BAR; PG8_WAIT_L(0); PG8_MMA(0, 0, At, B0); PG8_BAR; PG8_SCHED;
;             PG8_LDB(B1, 1, 1); PG8_STAGE(PG8_SB(1, 0), b3, voffB);
;             PG8_BAR; PG8_WAIT_L(0); PG8_MMA(0, 1, At, B1); PG8_BAR;
;             PG8_LDA(At, 1, 1); PG8_STAGE(PG8_SA(1, 0), a3, voffA);
.Lpw_p10_go:
	s_barrier
	s_setprio 1
	v_mfma_f32_16x16x32_bf16 v[54:57], v[200:203], v[168:171], 0
	v_mfma_f32_16x16x32_bf16 v[50:53], v[212:215], v[168:171], 0
	v_mfma_f32_16x16x32_bf16 v[38:41], v[200:203], v[176:179], 0
	v_mfma_f32_16x16x32_bf16 v[34:37], v[212:215], v[176:179], 0
	v_mfma_f32_16x16x32_bf16 v[22:25], v[200:203], v[184:187], 0
	v_mfma_f32_16x16x32_bf16 v[18:21], v[212:215], v[184:187], 0
	v_mfma_f32_16x16x32_bf16 v[6:9], v[200:203], v[192:195], 0
	v_mfma_f32_16x16x32_bf16 v[2:5], v[212:215], v[192:195], 0
	v_mfma_f32_16x16x32_bf16 v[54:57], v[208:211], v[172:175], v[54:57]
	v_mfma_f32_16x16x32_bf16 v[50:53], v[216:219], v[172:175], v[50:53]
	v_mfma_f32_16x16x32_bf16 v[38:41], v[208:211], v[180:183], v[38:41]
	v_mfma_f32_16x16x32_bf16 v[34:37], v[216:219], v[180:183], v[34:37]
	v_mfma_f32_16x16x32_bf16 v[22:25], v[208:211], v[188:191], v[22:25]
	v_mfma_f32_16x16x32_bf16 v[18:21], v[216:219], v[188:191], v[18:21]
	v_mfma_f32_16x16x32_bf16 v[6:9], v[208:211], v[196:199], v[6:9]
	v_mfma_f32_16x16x32_bf16 v[2:5], v[216:219], v[196:199], v[2:5]
	s_setprio 0
	s_add_i32 s50, 0, 0x18000
	v_add_u32_e32 v164, s50, v146
	s_barrier
	ds_read_b128 v[152:155], v164
	ds_read_b128 v[156:159], v164 offset:1024
	ds_read_b128 v[160:163], v164 offset:2048
	ds_read_b128 v[164:167], v164 offset:3072
	s_add_u32 s22, s22, 0x80000
	s_addc_u32 s23, s23, 0
	s_mov_b32 m0, s35
	v_lshl_add_u64 v[200:201], s[22:23], 0, v[130:131]
	ds_read_b128 v[168:171], v150 offset:32768
	ds_read_b128 v[172:175], v150 offset:33792
	ds_read_b128 v[176:179], v150 offset:34816
	ds_read_b128 v[180:183], v150 offset:35840
	ds_read_b128 v[184:187], v150 offset:36864
	ds_read_b128 v[188:191], v150 offset:37888
	ds_read_b128 v[192:195], v150 offset:38912
	ds_read_b128 v[196:199], v150 offset:39936
	global_load_lds_dwordx4 v[200:201], off
	v_lshl_add_u64 v[200:201], s[22:23], 0, v[134:135]
	s_mov_b32 m0, s36
	s_nop 0
	global_load_lds_dwordx4 v[200:201], off
	s_waitcnt lgkmcnt(8)
	s_barrier
	s_waitcnt lgkmcnt(0)
	s_setprio 1
	s_waitcnt lgkmcnt(0)
	v_mfma_f32_16x16x32_bf16 v[126:129], v[152:155], v[168:171], v[126:129]
	v_mfma_f32_16x16x32_bf16 v[122:125], v[160:163], v[168:171], v[122:125]
	v_mfma_f32_16x16x32_bf16 v[110:113], v[152:155], v[176:179], v[110:113]
	v_mfma_f32_16x16x32_bf16 v[106:109], v[160:163], v[176:179], v[106:109]
	v_mfma_f32_16x16x32_bf16 v[94:97], v[152:155], v[184:187], v[94:97]
	v_mfma_f32_16x16x32_bf16 v[90:93], v[160:163], v[184:187], v[90:93]
	v_mfma_f32_16x16x32_bf16 v[78:81], v[152:155], v[192:195], v[78:81]
	v_mfma_f32_16x16x32_bf16 v[74:77], v[160:163], v[192:195], v[74:77]
	v_mfma_f32_16x16x32_bf16 v[126:129], v[156:159], v[172:175], v[126:129]
	v_mfma_f32_16x16x32_bf16 v[122:125], v[164:167], v[172:175], v[122:125]
	v_mfma_f32_16x16x32_bf16 v[110:113], v[156:159], v[180:183], v[110:113]
	v_mfma_f32_16x16x32_bf16 v[106:109], v[164:167], v[180:183], v[106:109]
	v_mfma_f32_16x16x32_bf16 v[94:97], v[156:159], v[188:191], v[94:97]
	v_mfma_f32_16x16x32_bf16 v[90:93], v[164:167], v[188:191], v[90:93]
	v_mfma_f32_16x16x32_bf16 v[78:81], v[156:159], v[196:199], v[78:81]
	v_mfma_f32_16x16x32_bf16 v[74:77], v[164:167], v[196:199], v[74:77]
	s_setprio 0
	s_barrier
	s_add_i32 s22, 0, 0x1c000
	s_add_i32 s23, s50, s27
	v_add_u32_e32 v207, s22, v146
	v_lshl_add_u64 v[204:205], v[204:205], 0, s[6:7]
	s_mov_b32 m0, s23
	ds_read_b128 v[200:203], v207
	ds_read_b128 v[208:211], v207 offset:1024
	ds_read_b128 v[212:215], v207 offset:2048
	ds_read_b128 v[216:219], v207 offset:3072
	global_load_lds_dwordx4 v[204:205], off
	v_lshl_add_u64 v[204:205], v[220:221], 0, s[6:7]
	s_add_i32 m0, s23, 0x2000
	s_nop 0
	global_load_lds_dwordx4 v[204:205], off
	s_barrier
	s_waitcnt lgkmcnt(0)
	s_setprio 1
	s_waitcnt lgkmcnt(0)
	v_mfma_f32_16x16x32_bf16 v[118:121], v[200:203], v[168:171], v[118:121]
	v_mfma_f32_16x16x32_bf16 v[114:117], v[212:215], v[168:171], v[114:117]
	v_mfma_f32_16x16x32_bf16 v[102:105], v[200:203], v[176:179], v[102:105]
	v_mfma_f32_16x16x32_bf16 v[98:101], v[212:215], v[176:179], v[98:101]
	v_mfma_f32_16x16x32_bf16 v[86:89], v[200:203], v[184:187], v[86:89]
	v_mfma_f32_16x16x32_bf16 v[82:85], v[212:215], v[184:187], v[82:85]
	v_mfma_f32_16x16x32_bf16 v[70:73], v[200:203], v[192:195], v[70:73]
	v_mfma_f32_16x16x32_bf16 v[66:69], v[212:215], v[192:195], v[66:69]
	v_mfma_f32_16x16x32_bf16 v[118:121], v[208:211], v[172:175], v[118:121]
	v_mfma_f32_16x16x32_bf16 v[114:117], v[216:219], v[172:175], v[114:117]
	v_mfma_f32_16x16x32_bf16 v[102:105], v[208:211], v[180:183], v[102:105]
	v_mfma_f32_16x16x32_bf16 v[98:101], v[216:219], v[180:183], v[98:101]
	v_mfma_f32_16x16x32_bf16 v[86:89], v[208:211], v[188:191], v[86:89]
	v_mfma_f32_16x16x32_bf16 v[82:85], v[216:219], v[188:191], v[82:85]
	v_mfma_f32_16x16x32_bf16 v[70:73], v[208:211], v[196:199], v[70:73]
	v_mfma_f32_16x16x32_bf16 v[66:69], v[216:219], v[196:199], v[66:69]
	s_setprio 0
	s_mov_b32 m0, s37
	v_lshl_add_u64 v[204:205], v[222:223], 0, s[6:7]
	s_barrier
	ds_read_b128 v[168:171], v150 offset:49152
	ds_read_b128 v[172:175], v150 offset:50176
	ds_read_b128 v[176:179], v150 offset:51200
	ds_read_b128 v[180:183], v150 offset:52224
	ds_read_b128 v[184:187], v150 offset:53248
	ds_read_b128 v[188:191], v150 offset:54272
	ds_read_b128 v[192:195], v150 offset:55296
	ds_read_b128 v[196:199], v150 offset:56320
	global_load_lds_dwordx4 v[204:205], off
	v_lshl_add_u64 v[204:205], v[224:225], 0, s[6:7]
	s_mov_b32 m0, s38
	s_nop 0
	global_load_lds_dwordx4 v[204:205], off
	s_barrier
; #define PG8_STAGE(bufoff, gbase, voff) do { _Pragma("unroll") for (int _i = 0; _i < 2; ++_i) \
;         __builtin_amdgcn_global_load_lds((const unsigned*)((const char*)(gbase) + (voff)[_i]), (LAS unsigned*)(lds + (bufoff) + ldsw + _i * 8192), 16, 0, 0); } while (0)
; #define PG8_LDA(dst, b, h) do { _Pragma("unroll") for (int m = 0; m < 4; ++m) _Pragma("unroll") for (int k = 0; k < 2; ++k) dst[m][k] = *(const LAS bf16x8*)(lds + PG8_SA(b, h) + aoff + m * 2048 + k * 1024); } while (0)
; #define PG8_LDB(dst, b, h) do { _Pragma("unroll") for (int n = 0; n < 2; ++n) _Pragma("unroll") for (int k = 0; k < 2; ++k) dst[n][k] = *(const LAS bf16x8*)(lds + PG8_SB(b, h) + boff + n * 2048 + k * 1024); } while (0)
; #define PG8_MMA(ai, bj, At, Bt) do { __builtin_amdgcn_s_setprio(1); _Pragma("unroll") for (int m = 0; m < 4; ++m) _Pragma("unroll") for (int n = 0; n < 2; ++n) _Pragma("unroll") for (int k = 0; k < 2; ++k) \
;         acc[ai][bj][m][n] = __builtin_amdgcn_mfma_f32_16x16x32_bf16(Bt[n][k], At[m][k], acc[ai][bj][m][n], 0, 0, 0); __builtin_amdgcn_s_setprio(0); } while (0)
; #define PG8_WAIT_V(n) asm volatile("s_waitcnt vmcnt(" #n ")" ::: "memory")
; #define PG8_WAIT_L(n) asm volatile("s_waitcnt lgkmcnt(" #n ")" ::: "memory")
; #define PG8_BAR __builtin_amdgcn_s_barrier()
; #define PG8_SCHED __builtin_amdgcn_sched_barrier(0)
; template <class Epi, class Sched>
; __device__ __forceinline__ void gemm_phase(LAS unsigned char* lds, const Gemm g, const Sched& S, const Epi& E) {
;     ...
;             PG8_LDB(B0, 0, 0); PG8_SCHED; PG8_LDA(At, 0, 0); PG8_STAGE(PG8_SA(1, 1), a1 + hstep, voffA);
;             PG8_WAIT_L(8); PG8_BAR; PG8_WAIT_L(0); PG8_MMA(0, 0, At, B0); PG8_BAR; PG8_SCHED;
;             PG8_LDB(B1, 0, 1); PG8_STAGE(PG8_SB(0, 0), b2, voffB);
;     ...
;             PG8_BAR; PG8_WAIT_L(0); PG8_MMA(0, 1, At, B1); PG8_BAR;
;             PG8_LDA(At, 1, 1); PG8_STAGE(PG8_SA(1, 0), a3, voffA);
;             PG8_BAR; PG8_WAIT_L(0); PG8_MMA(1, 0, At, B0); PG8_BAR; PG8_SCHED;
;             PG8_STAGE(PG8_SB(1, 1), b3 + hstep, voffB);
;             PG8_WAIT_V(6); PG8_BAR; PG8_MMA(1, 1, At, B1); PG8_BAR;
	s_waitcnt lgkmcnt(0)
	s_setprio 1
	s_waitcnt lgkmcnt(0)
	v_mfma_f32_16x16x32_bf16 v[62:65], v[152:155], v[168:171], v[62:65]
	v_mfma_f32_16x16x32_bf16 v[58:61], v[160:163], v[168:171], v[58:61]
	v_mfma_f32_16x16x32_bf16 v[46:49], v[152:155], v[176:179], v[46:49]
	v_mfma_f32_16x16x32_bf16 v[42:45], v[160:163], v[176:179], v[42:45]
	v_mfma_f32_16x16x32_bf16 v[30:33], v[152:155], v[184:187], v[30:33]
	v_mfma_f32_16x16x32_bf16 v[26:29], v[160:163], v[184:187], v[26:29]
	v_mfma_f32_16x16x32_bf16 v[14:17], v[152:155], v[192:195], v[14:17]
	v_mfma_f32_16x16x32_bf16 v[10:13], v[160:163], v[192:195], v[10:13]
	v_mfma_f32_16x16x32_bf16 v[62:65], v[156:159], v[172:175], v[62:65]
	v_mfma_f32_16x16x32_bf16 v[58:61], v[164:167], v[172:175], v[58:61]
	v_mfma_f32_16x16x32_bf16 v[46:49], v[156:159], v[180:183], v[46:49]
	v_mfma_f32_16x16x32_bf16 v[42:45], v[164:167], v[180:183], v[42:45]
	v_mfma_f32_16x16x32_bf16 v[30:33], v[156:159], v[188:191], v[30:33]
	v_mfma_f32_16x16x32_bf16 v[26:29], v[164:167], v[188:191], v[26:29]
	v_mfma_f32_16x16x32_bf16 v[14:17], v[156:159], v[196:199], v[14:17]
	v_mfma_f32_16x16x32_bf16 v[10:13], v[164:167], v[196:199], v[10:13]
	s_setprio 0
	s_barrier
	s_add_u32 s20, s20, 0x80080
	s_addc_u32 s21, s21, 0
	s_add_i32 s22, s22, s27
	v_lshl_add_u64 v[152:153], s[20:21], 0, v[132:133]
	s_mov_b32 m0, s22
	s_nop 0
	global_load_lds_dwordx4 v[152:153], off
	v_lshl_add_u64 v[152:153], s[20:21], 0, v[136:137]
	s_add_i32 m0, s22, 0x2000
	s_nop 0
	global_load_lds_dwordx4 v[152:153], off
	s_waitcnt vmcnt(6)
	s_barrier
	s_setprio 1
	v_mfma_f32_16x16x32_bf16 v[54:57], v[200:203], v[168:171], v[54:57]
	v_mfma_f32_16x16x32_bf16 v[50:53], v[212:215], v[168:171], v[50:53]
	v_mfma_f32_16x16x32_bf16 v[38:41], v[200:203], v[176:179], v[38:41]
	v_mfma_f32_16x16x32_bf16 v[34:37], v[212:215], v[176:179], v[34:37]
	v_mfma_f32_16x16x32_bf16 v[22:25], v[200:203], v[184:187], v[22:25]
	v_mfma_f32_16x16x32_bf16 v[18:21], v[212:215], v[184:187], v[18:21]
	v_mfma_f32_16x16x32_bf16 v[6:9], v[200:203], v[192:195], v[6:9]
	v_mfma_f32_16x16x32_bf16 v[2:5], v[212:215], v[192:195], v[2:5]
	v_mfma_f32_16x16x32_bf16 v[54:57], v[208:211], v[172:175], v[54:57]
	v_mfma_f32_16x16x32_bf16 v[50:53], v[216:219], v[172:175], v[50:53]
	v_mfma_f32_16x16x32_bf16 v[38:41], v[208:211], v[180:183], v[38:41]
	v_mfma_f32_16x16x32_bf16 v[34:37], v[216:219], v[180:183], v[34:37]
	v_mfma_f32_16x16x32_bf16 v[22:25], v[208:211], v[188:191], v[22:25]
	v_mfma_f32_16x16x32_bf16 v[18:21], v[216:219], v[188:191], v[18:21]
	v_mfma_f32_16x16x32_bf16 v[6:9], v[208:211], v[196:199], v[6:9]
	v_mfma_f32_16x16x32_bf16 v[2:5], v[216:219], v[196:199], v[2:5]
	s_setprio 0
	s_add_i32 s49, s49, 2
	s_add_u32 s18, s18, 0x100
	s_addc_u32 s19, s19, 0
	s_add_u32 s47, s47, 0x100
	s_addc_u32 s48, s48, 0
	s_cmp_gt_u32 s49, 29
	s_barrier
.LBB0_1091:
	ds_read_b128 v[152:155], v149
	ds_read_b128 v[156:159], v149 offset:1024
	ds_read_b128 v[160:163], v149 offset:2048
	ds_read_b128 v[164:167], v149 offset:3072
	s_add_u32 s20, s18, 0xfff80080
	s_addc_u32 s21, s19, -1
	s_cmp_eq_u32 s49, 28
	s_cselect_b32 s23, s11, s21
	s_cselect_b32 s22, s45, s20
	s_cselect_b32 s21, s9, s48
	s_cselect_b32 s20, s46, s47
	v_lshl_add_u64 v[200:201], s[18:19], 0, v[138:139]
	s_add_i32 m0, s17, 0xc000
	ds_read_b128 v[168:171], v150
	ds_read_b128 v[172:175], v150 offset:1024
	ds_read_b128 v[176:179], v150 offset:2048
	ds_read_b128 v[180:183], v150 offset:3072
	ds_read_b128 v[184:187], v150 offset:4096
	ds_read_b128 v[188:191], v150 offset:5120
	ds_read_b128 v[192:195], v150 offset:6144
	ds_read_b128 v[196:199], v150 offset:7168
	global_load_lds_dwordx4 v[200:201], off
	v_lshl_add_u64 v[200:201], s[18:19], 0, v[140:141]
	s_add_i32 m0, s17, 0xe000
	s_nop 0
	global_load_lds_dwordx4 v[200:201], off
	s_waitcnt lgkmcnt(8)
	s_barrier
	s_waitcnt lgkmcnt(0)
	s_setprio 1
	s_waitcnt lgkmcnt(0)
	v_mfma_f32_16x16x32_bf16 v[126:129], v[152:155], v[168:171], v[126:129]
	v_mfma_f32_16x16x32_bf16 v[122:125], v[160:163], v[168:171], v[122:125]
	v_mfma_f32_16x16x32_bf16 v[110:113], v[152:155], v[176:179], v[110:113]
	v_mfma_f32_16x16x32_bf16 v[106:109], v[160:163], v[176:179], v[106:109]
	v_mfma_f32_16x16x32_bf16 v[94:97], v[152:155], v[184:187], v[94:97]
	v_mfma_f32_16x16x32_bf16 v[90:93], v[160:163], v[184:187], v[90:93]
	v_mfma_f32_16x16x32_bf16 v[78:81], v[152:155], v[192:195], v[78:81]
	v_mfma_f32_16x16x32_bf16 v[74:77], v[160:163], v[192:195], v[74:77]
	v_mfma_f32_16x16x32_bf16 v[126:129], v[156:159], v[172:175], v[126:129]
	v_mfma_f32_16x16x32_bf16 v[122:125], v[164:167], v[172:175], v[122:125]
	v_mfma_f32_16x16x32_bf16 v[110:113], v[156:159], v[180:183], v[110:113]
	v_mfma_f32_16x16x32_bf16 v[106:109], v[164:167], v[180:183], v[106:109]
	v_mfma_f32_16x16x32_bf16 v[94:97], v[156:159], v[188:191], v[94:97]
	v_mfma_f32_16x16x32_bf16 v[90:93], v[164:167], v[188:191], v[90:93]
	v_mfma_f32_16x16x32_bf16 v[78:81], v[156:159], v[196:199], v[78:81]
	v_mfma_f32_16x16x32_bf16 v[74:77], v[164:167], v[196:199], v[74:77]
	s_setprio 0
	s_barrier
	s_add_i32 s50, s39, s27
	v_lshl_add_u64 v[204:205], s[20:21], 0, v[132:133]
	s_mov_b32 m0, s50
	ds_read_b128 v[200:203], v151
	ds_read_b128 v[208:211], v151 offset:1024
	ds_read_b128 v[212:215], v151 offset:2048
	ds_read_b128 v[216:219], v151 offset:3072
	global_load_lds_dwordx4 v[204:205], off
	v_lshl_add_u64 v[220:221], s[20:21], 0, v[136:137]
	s_add_i32 m0, s50, 0x2000
	s_nop 0
	global_load_lds_dwordx4 v[220:221], off
	s_barrier
; #define PG8_STAGE(bufoff, gbase, voff) do { _Pragma("unroll") for (int _i = 0; _i < 2; ++_i) \
;         __builtin_amdgcn_global_load_lds((const unsigned*)((const char*)(gbase) + (voff)[_i]), (LAS unsigned*)(lds + (bufoff) + ldsw + _i * 8192), 16, 0, 0); } while (0)
; #define PG8_LDA(dst, b, h) do { _Pragma("unroll") for (int m = 0; m < 4; ++m) _Pragma("unroll") for (int k = 0; k < 2; ++k) dst[m][k] = *(const LAS bf16x8*)(lds + PG8_SA(b, h) + aoff + m * 2048 + k * 1024); } while (0)
; #define PG8_LDB(dst, b, h) do { _Pragma("unroll") for (int n = 0; n < 2; ++n) _Pragma("unroll") for (int k = 0; k < 2; ++k) dst[n][k] = *(const LAS bf16x8*)(lds + PG8_SB(b, h) + boff + n * 2048 + k * 1024); } while (0)
; #define PG8_MMA(ai, bj, At, Bt) do { __builtin_amdgcn_s_setprio(1); _Pragma("unroll") for (int m = 0; m < 4; ++m) _Pragma("unroll") for (int n = 0; n < 2; ++n) _Pragma("unroll") for (int k = 0; k < 2; ++k) \
;         acc[ai][bj][m][n] = __builtin_amdgcn_mfma_f32_16x16x32_bf16(Bt[n][k], At[m][k], acc[ai][bj][m][n], 0, 0, 0); __builtin_amdgcn_s_setprio(0); } while (0)
; #define PG8_WAIT_V(n) asm volatile("s_waitcnt vmcnt(" #n ")" ::: "memory")
; #define PG8_WAIT_L(n) asm volatile("s_waitcnt lgkmcnt(" #n ")" ::: "memory")
; #define PG8_BAR __builtin_amdgcn_s_barrier()
; #define PG8_SCHED __builtin_amdgcn_sched_barrier(0)
; template <class Epi, class Sched>
; __device__ __forceinline__ void gemm_phase(LAS unsigned char* lds, const Gemm g, const Sched& S, const Epi& E) {
;     ...
;             PG8_BAR; PG8_WAIT_L(0); PG8_MMA(0, 1, At, B1); PG8_BAR;
;             PG8_LDA(At, 0, 1); PG8_STAGE(PG8_SA(0, 0), a2, voffA);
;             PG8_BAR; PG8_WAIT_L(0); PG8_MMA(1, 0, At, B0); PG8_BAR; PG8_SCHED;
;             PG8_STAGE(PG8_SB(0, 1), b2 + hstep, voffB);
;             PG8_WAIT_V(6); PG8_BAR; PG8_MMA(1, 1, At, B1); PG8_BAR;
;             PG8_LDB(B0, 1, 0); PG8_SCHED; PG8_LDA(At, 1, 0); PG8_STAGE(PG8_SA(0, 1), a2 + hstep, voffA);
;             PG8_WAIT_L(8); PG8_BAR; PG8_WAIT_L(0); PG8_MMA(0, 0, At, B0); PG8_BAR; PG8_SCHED;
	s_waitcnt lgkmcnt(0)
	s_setprio 1
	s_waitcnt lgkmcnt(0)
	v_mfma_f32_16x16x32_bf16 v[118:121], v[200:203], v[168:171], v[118:121]
	v_mfma_f32_16x16x32_bf16 v[114:117], v[212:215], v[168:171], v[114:117]
	v_mfma_f32_16x16x32_bf16 v[102:105], v[200:203], v[176:179], v[102:105]
	v_mfma_f32_16x16x32_bf16 v[98:101], v[212:215], v[176:179], v[98:101]
	v_mfma_f32_16x16x32_bf16 v[86:89], v[200:203], v[184:187], v[86:89]
	v_mfma_f32_16x16x32_bf16 v[82:85], v[212:215], v[184:187], v[82:85]
	v_mfma_f32_16x16x32_bf16 v[70:73], v[200:203], v[192:195], v[70:73]
	v_mfma_f32_16x16x32_bf16 v[66:69], v[212:215], v[192:195], v[66:69]
	v_mfma_f32_16x16x32_bf16 v[118:121], v[208:211], v[172:175], v[118:121]
	v_mfma_f32_16x16x32_bf16 v[114:117], v[216:219], v[172:175], v[114:117]
	v_mfma_f32_16x16x32_bf16 v[102:105], v[208:211], v[180:183], v[102:105]
	v_mfma_f32_16x16x32_bf16 v[98:101], v[216:219], v[180:183], v[98:101]
	v_mfma_f32_16x16x32_bf16 v[86:89], v[208:211], v[188:191], v[86:89]
	v_mfma_f32_16x16x32_bf16 v[82:85], v[216:219], v[188:191], v[82:85]
	v_mfma_f32_16x16x32_bf16 v[70:73], v[208:211], v[196:199], v[70:73]
	v_mfma_f32_16x16x32_bf16 v[66:69], v[216:219], v[196:199], v[66:69]
	s_setprio 0
	s_mov_b32 m0, s17
	v_lshl_add_u64 v[222:223], s[22:23], 0, v[130:131]
	s_barrier
	ds_read_b128 v[168:171], v150 offset:16384
	ds_read_b128 v[172:175], v150 offset:17408
	ds_read_b128 v[176:179], v150 offset:18432
	ds_read_b128 v[180:183], v150 offset:19456
	ds_read_b128 v[184:187], v150 offset:20480
	ds_read_b128 v[188:191], v150 offset:21504
	ds_read_b128 v[192:195], v150 offset:22528
	ds_read_b128 v[196:199], v150 offset:23552
	global_load_lds_dwordx4 v[222:223], off
	v_lshl_add_u64 v[224:225], s[22:23], 0, v[134:135]
	s_mov_b32 m0, s34
	s_nop 0
	global_load_lds_dwordx4 v[224:225], off
	s_barrier
	s_waitcnt lgkmcnt(0)
	s_setprio 1
	s_waitcnt lgkmcnt(0)
	v_mfma_f32_16x16x32_bf16 v[62:65], v[152:155], v[168:171], v[62:65]
	v_mfma_f32_16x16x32_bf16 v[58:61], v[160:163], v[168:171], v[58:61]
	v_mfma_f32_16x16x32_bf16 v[46:49], v[152:155], v[176:179], v[46:49]
	v_mfma_f32_16x16x32_bf16 v[42:45], v[160:163], v[176:179], v[42:45]
	v_mfma_f32_16x16x32_bf16 v[30:33], v[152:155], v[184:187], v[30:33]
	v_mfma_f32_16x16x32_bf16 v[26:29], v[160:163], v[184:187], v[26:29]
	v_mfma_f32_16x16x32_bf16 v[14:17], v[152:155], v[192:195], v[14:17]
	v_mfma_f32_16x16x32_bf16 v[10:13], v[160:163], v[192:195], v[10:13]
	v_mfma_f32_16x16x32_bf16 v[62:65], v[156:159], v[172:175], v[62:65]
	v_mfma_f32_16x16x32_bf16 v[58:61], v[164:167], v[172:175], v[58:61]
	v_mfma_f32_16x16x32_bf16 v[46:49], v[156:159], v[180:183], v[46:49]
	v_mfma_f32_16x16x32_bf16 v[42:45], v[164:167], v[180:183], v[42:45]
	v_mfma_f32_16x16x32_bf16 v[30:33], v[156:159], v[188:191], v[30:33]
	v_mfma_f32_16x16x32_bf16 v[26:29], v[164:167], v[188:191], v[26:29]
	v_mfma_f32_16x16x32_bf16 v[14:17], v[156:159], v[196:199], v[14:17]
	v_mfma_f32_16x16x32_bf16 v[10:13], v[164:167], v[196:199], v[10:13]
	s_setprio 0
	s_barrier
	s_add_u32 s50, s20, 0x80000
	s_addc_u32 s51, s21, 0
	s_add_i32 s52, s40, s27
	v_lshl_add_u64 v[152:153], s[50:51], 0, v[132:133]
	s_mov_b32 m0, s52
	s_nop 0
	global_load_lds_dwordx4 v[152:153], off
	v_lshl_add_u64 v[152:153], s[50:51], 0, v[136:137]
	s_add_i32 m0, s52, 0x2000
	s_nop 0
	global_load_lds_dwordx4 v[152:153], off
	s_waitcnt vmcnt(6)
	s_barrier
	s_setprio 1
	v_mfma_f32_16x16x32_bf16 v[54:57], v[200:203], v[168:171], v[54:57]
	v_mfma_f32_16x16x32_bf16 v[50:53], v[212:215], v[168:171], v[50:53]
	v_mfma_f32_16x16x32_bf16 v[38:41], v[200:203], v[176:179], v[38:41]
	v_mfma_f32_16x16x32_bf16 v[34:37], v[212:215], v[176:179], v[34:37]
	v_mfma_f32_16x16x32_bf16 v[22:25], v[200:203], v[184:187], v[22:25]
	v_mfma_f32_16x16x32_bf16 v[18:21], v[212:215], v[184:187], v[18:21]
	v_mfma_f32_16x16x32_bf16 v[6:9], v[200:203], v[192:195], v[6:9]
	v_mfma_f32_16x16x32_bf16 v[2:5], v[212:215], v[192:195], v[2:5]
	v_mfma_f32_16x16x32_bf16 v[54:57], v[208:211], v[172:175], v[54:57]
	v_mfma_f32_16x16x32_bf16 v[50:53], v[216:219], v[172:175], v[50:53]
	v_mfma_f32_16x16x32_bf16 v[38:41], v[208:211], v[180:183], v[38:41]
	v_mfma_f32_16x16x32_bf16 v[34:37], v[216:219], v[180:183], v[34:37]
	v_mfma_f32_16x16x32_bf16 v[22:25], v[208:211], v[188:191], v[22:25]
	v_mfma_f32_16x16x32_bf16 v[18:21], v[216:219], v[188:191], v[18:21]
	v_mfma_f32_16x16x32_bf16 v[6:9], v[208:211], v[196:199], v[6:9]
	v_mfma_f32_16x16x32_bf16 v[2:5], v[216:219], v[196:199], v[2:5]
	s_setprio 0
	s_add_i32 s50, 0, 0x18000
	v_add_u32_e32 v164, s50, v146
	s_barrier
	ds_read_b128 v[152:155], v164
	ds_read_b128 v[156:159], v164 offset:1024
	ds_read_b128 v[160:163], v164 offset:2048
	ds_read_b128 v[164:167], v164 offset:3072
	s_add_u32 s22, s22, 0x80000
	s_addc_u32 s23, s23, 0
	s_mov_b32 m0, s35
	v_lshl_add_u64 v[200:201], s[22:23], 0, v[130:131]
	ds_read_b128 v[168:171], v150 offset:32768
	ds_read_b128 v[172:175], v150 offset:33792
	ds_read_b128 v[176:179], v150 offset:34816
	ds_read_b128 v[180:183], v150 offset:35840
	ds_read_b128 v[184:187], v150 offset:36864
	ds_read_b128 v[188:191], v150 offset:37888
	ds_read_b128 v[192:195], v150 offset:38912
	ds_read_b128 v[196:199], v150 offset:39936
	global_load_lds_dwordx4 v[200:201], off
	v_lshl_add_u64 v[200:201], s[22:23], 0, v[134:135]
	s_mov_b32 m0, s36
	s_nop 0
	global_load_lds_dwordx4 v[200:201], off
	s_waitcnt lgkmcnt(8)
	s_barrier
; #define PG8_STAGE(bufoff, gbase, voff) do { _Pragma("unroll") for (int _i = 0; _i < 2; ++_i) \
;         __builtin_amdgcn_global_load_lds((const unsigned*)((const char*)(gbase) + (voff)[_i]), (LAS unsigned*)(lds + (bufoff) + ldsw + _i * 8192), 16, 0, 0); } while (0)
; #define PG8_LDA(dst, b, h) do { _Pragma("unroll") for (int m = 0; m < 4; ++m) _Pragma("unroll") for (int k = 0; k < 2; ++k) dst[m][k] = *(const LAS bf16x8*)(lds + PG8_SA(b, h) + aoff + m * 2048 + k * 1024); } while (0)
; #define PG8_LDB(dst, b, h) do { _Pragma("unroll") for (int n = 0; n < 2; ++n) _Pragma("unroll") for (int k = 0; k < 2; ++k) dst[n][k] = *(const LAS bf16x8*)(lds + PG8_SB(b, h) + boff + n * 2048 + k * 1024); } while (0)
; #define PG8_MMA(ai, bj, At, Bt) do { __builtin_amdgcn_s_setprio(1); _Pragma("unroll") for (int m = 0; m < 4; ++m) _Pragma("unroll") for (int n = 0; n < 2; ++n) _Pragma("unroll") for (int k = 0; k < 2; ++k) \
;         acc[ai][bj][m][n] = __builtin_amdgcn_mfma_f32_16x16x32_bf16(Bt[n][k], At[m][k], acc[ai][bj][m][n], 0, 0, 0); __builtin_amdgcn_s_setprio(0); } while (0)
; #define PG8_WAIT_V(n) asm volatile("s_waitcnt vmcnt(" #n ")" ::: "memory")
; #define PG8_WAIT_L(n) asm volatile("s_waitcnt lgkmcnt(" #n ")" ::: "memory")
; #define PG8_BAR __builtin_amdgcn_s_barrier()
; #define PG8_SCHED __builtin_amdgcn_sched_barrier(0)
; template <class Epi, class Sched>
; __device__ __forceinline__ void gemm_phase(LAS unsigned char* lds, const Gemm g, const Sched& S, const Epi& E) {
;     ...
;             PG8_WAIT_L(8); PG8_BAR; PG8_WAIT_L(0); PG8_MMA(0, 0, At, B0); PG8_BAR; PG8_SCHED;
;             PG8_LDB(B1, 1, 1); PG8_STAGE(PG8_SB(1, 0), b3, voffB);
;             PG8_BAR; PG8_WAIT_L(0); PG8_MMA(0, 1, At, B1); PG8_BAR;
;             PG8_LDA(At, 1, 1); PG8_STAGE(PG8_SA(1, 0), a3, voffA);
;             PG8_BAR; PG8_WAIT_L(0); PG8_MMA(1, 0, At, B0); PG8_BAR; PG8_SCHED;
;             PG8_STAGE(PG8_SB(1, 1), b3 + hstep, voffB);
;             PG8_WAIT_V(6); PG8_BAR; PG8_MMA(1, 1, At, B1); PG8_BAR;
	s_waitcnt lgkmcnt(0)
	s_setprio 1
	s_waitcnt lgkmcnt(0)
	v_mfma_f32_16x16x32_bf16 v[126:129], v[152:155], v[168:171], v[126:129]
	v_mfma_f32_16x16x32_bf16 v[122:125], v[160:163], v[168:171], v[122:125]
	v_mfma_f32_16x16x32_bf16 v[110:113], v[152:155], v[176:179], v[110:113]
	v_mfma_f32_16x16x32_bf16 v[106:109], v[160:163], v[176:179], v[106:109]
	v_mfma_f32_16x16x32_bf16 v[94:97], v[152:155], v[184:187], v[94:97]
	v_mfma_f32_16x16x32_bf16 v[90:93], v[160:163], v[184:187], v[90:93]
	v_mfma_f32_16x16x32_bf16 v[78:81], v[152:155], v[192:195], v[78:81]
	v_mfma_f32_16x16x32_bf16 v[74:77], v[160:163], v[192:195], v[74:77]
	v_mfma_f32_16x16x32_bf16 v[126:129], v[156:159], v[172:175], v[126:129]
	v_mfma_f32_16x16x32_bf16 v[122:125], v[164:167], v[172:175], v[122:125]
	v_mfma_f32_16x16x32_bf16 v[110:113], v[156:159], v[180:183], v[110:113]
	v_mfma_f32_16x16x32_bf16 v[106:109], v[164:167], v[180:183], v[106:109]
	v_mfma_f32_16x16x32_bf16 v[94:97], v[156:159], v[188:191], v[94:97]
	v_mfma_f32_16x16x32_bf16 v[90:93], v[164:167], v[188:191], v[90:93]
	v_mfma_f32_16x16x32_bf16 v[78:81], v[156:159], v[196:199], v[78:81]
	v_mfma_f32_16x16x32_bf16 v[74:77], v[164:167], v[196:199], v[74:77]
	s_setprio 0
	s_barrier
	s_add_i32 s22, 0, 0x1c000
	s_add_i32 s23, s50, s27
	v_add_u32_e32 v207, s22, v146
	v_lshl_add_u64 v[204:205], v[204:205], 0, s[6:7]
	s_mov_b32 m0, s23
	ds_read_b128 v[200:203], v207
	ds_read_b128 v[208:211], v207 offset:1024
	ds_read_b128 v[212:215], v207 offset:2048
	ds_read_b128 v[216:219], v207 offset:3072
	global_load_lds_dwordx4 v[204:205], off
	v_lshl_add_u64 v[204:205], v[220:221], 0, s[6:7]
	s_add_i32 m0, s23, 0x2000
	s_nop 0
	global_load_lds_dwordx4 v[204:205], off
	s_barrier
	s_waitcnt lgkmcnt(0)
	s_setprio 1
	s_waitcnt lgkmcnt(0)
	v_mfma_f32_16x16x32_bf16 v[118:121], v[200:203], v[168:171], v[118:121]
	v_mfma_f32_16x16x32_bf16 v[114:117], v[212:215], v[168:171], v[114:117]
	v_mfma_f32_16x16x32_bf16 v[102:105], v[200:203], v[176:179], v[102:105]
	v_mfma_f32_16x16x32_bf16 v[98:101], v[212:215], v[176:179], v[98:101]
	v_mfma_f32_16x16x32_bf16 v[86:89], v[200:203], v[184:187], v[86:89]
	v_mfma_f32_16x16x32_bf16 v[82:85], v[212:215], v[184:187], v[82:85]
	v_mfma_f32_16x16x32_bf16 v[70:73], v[200:203], v[192:195], v[70:73]
	v_mfma_f32_16x16x32_bf16 v[66:69], v[212:215], v[192:195], v[66:69]
	v_mfma_f32_16x16x32_bf16 v[118:121], v[208:211], v[172:175], v[118:121]
	v_mfma_f32_16x16x32_bf16 v[114:117], v[216:219], v[172:175], v[114:117]
	v_mfma_f32_16x16x32_bf16 v[102:105], v[208:211], v[180:183], v[102:105]
	v_mfma_f32_16x16x32_bf16 v[98:101], v[216:219], v[180:183], v[98:101]
	v_mfma_f32_16x16x32_bf16 v[86:89], v[208:211], v[188:191], v[86:89]
	v_mfma_f32_16x16x32_bf16 v[82:85], v[216:219], v[188:191], v[82:85]
	v_mfma_f32_16x16x32_bf16 v[70:73], v[208:211], v[196:199], v[70:73]
	v_mfma_f32_16x16x32_bf16 v[66:69], v[216:219], v[196:199], v[66:69]
	s_setprio 0
	s_mov_b32 m0, s37
	v_lshl_add_u64 v[204:205], v[222:223], 0, s[6:7]
	s_barrier
	ds_read_b128 v[168:171], v150 offset:49152
	ds_read_b128 v[172:175], v150 offset:50176
	ds_read_b128 v[176:179], v150 offset:51200
	ds_read_b128 v[180:183], v150 offset:52224
	ds_read_b128 v[184:187], v150 offset:53248
	ds_read_b128 v[188:191], v150 offset:54272
	ds_read_b128 v[192:195], v150 offset:55296
	ds_read_b128 v[196:199], v150 offset:56320
	global_load_lds_dwordx4 v[204:205], off
	v_lshl_add_u64 v[204:205], v[224:225], 0, s[6:7]
	s_mov_b32 m0, s38
	s_nop 0
	global_load_lds_dwordx4 v[204:205], off
	s_barrier
	s_waitcnt lgkmcnt(0)
	s_setprio 1
	s_waitcnt lgkmcnt(0)
	v_mfma_f32_16x16x32_bf16 v[62:65], v[152:155], v[168:171], v[62:65]
	v_mfma_f32_16x16x32_bf16 v[58:61], v[160:163], v[168:171], v[58:61]
	v_mfma_f32_16x16x32_bf16 v[46:49], v[152:155], v[176:179], v[46:49]
	v_mfma_f32_16x16x32_bf16 v[42:45], v[160:163], v[176:179], v[42:45]
	v_mfma_f32_16x16x32_bf16 v[30:33], v[152:155], v[184:187], v[30:33]
	v_mfma_f32_16x16x32_bf16 v[26:29], v[160:163], v[184:187], v[26:29]
	v_mfma_f32_16x16x32_bf16 v[14:17], v[152:155], v[192:195], v[14:17]
	v_mfma_f32_16x16x32_bf16 v[10:13], v[160:163], v[192:195], v[10:13]
	v_mfma_f32_16x16x32_bf16 v[62:65], v[156:159], v[172:175], v[62:65]
	v_mfma_f32_16x16x32_bf16 v[58:61], v[164:167], v[172:175], v[58:61]
	v_mfma_f32_16x16x32_bf16 v[46:49], v[156:159], v[180:183], v[46:49]
	v_mfma_f32_16x16x32_bf16 v[42:45], v[164:167], v[180:183], v[42:45]
	v_mfma_f32_16x16x32_bf16 v[30:33], v[156:159], v[188:191], v[30:33]
	v_mfma_f32_16x16x32_bf16 v[26:29], v[164:167], v[188:191], v[26:29]
	v_mfma_f32_16x16x32_bf16 v[14:17], v[156:159], v[196:199], v[14:17]
	v_mfma_f32_16x16x32_bf16 v[10:13], v[164:167], v[196:199], v[10:13]
	s_setprio 0
	s_barrier
	s_add_u32 s20, s20, 0x80080
	s_addc_u32 s21, s21, 0
	s_add_i32 s22, s22, s27
	v_lshl_add_u64 v[152:153], s[20:21], 0, v[132:133]
	s_mov_b32 m0, s22
	s_nop 0
	global_load_lds_dwordx4 v[152:153], off
	v_lshl_add_u64 v[152:153], s[20:21], 0, v[136:137]
	s_add_i32 m0, s22, 0x2000
	s_nop 0
	global_load_lds_dwordx4 v[152:153], off
	s_cmp_eq_u32 s49, 28
	s_cbranch_scc0 .Lxs_p10_n
	s_add_u32 s20, s45, 0x80080
	s_addc_u32 s21, s11, 0
	v_lshl_add_u64 v[152:153], s[20:21], 0, v[138:139]
	s_add_i32 m0, s17, 0xc000
	s_nop 0
	global_load_lds_dwordx4 v[152:153], off
	v_lshl_add_u64 v[152:153], s[20:21], 0, v[140:141]
	s_add_i32 m0, s17, 0xe000
	s_nop 0
	global_load_lds_dwordx4 v[152:153], off
	s_waitcnt vmcnt(8)
	s_branch .Lxs_p10_j

; #define LAS __attribute__((address_space(3)))
; DI unsigned pk2(float a, float b) { f32x2_t v = {a, b}; return __builtin_bit_cast(unsigned, __builtin_convertvector(v, bf16x2_t)); }
; #define PG8_MMA(ai, bj, At, Bt) do { __builtin_amdgcn_s_setprio(1); _Pragma("unroll") for (int m = 0; m < 4; ++m) _Pragma("unroll") for (int n = 0; n < 2; ++n) _Pragma("unroll") for (int k = 0; k < 2; ++k) \
;         acc[ai][bj][m][n] = __builtin_amdgcn_mfma_f32_16x16x32_bf16(Bt[n][k], At[m][k], acc[ai][bj][m][n], 0, 0, 0); __builtin_amdgcn_s_setprio(0); } while (0)
; #define PG8_WAIT_V(n) asm volatile("s_waitcnt vmcnt(" #n ")" ::: "memory")
; #define PG8_BAR __builtin_amdgcn_s_barrier()
; template <class Epi, class Sched>
; __device__ __forceinline__ void gemm_phase(LAS unsigned char* lds, const Gemm g, const Sched& S, const Epi& E) {
;     ...
;             PG8_WAIT_V(6); PG8_BAR; PG8_MMA(1, 1, At, B1); PG8_BAR;
;         }
;     DI void operator()(const f32x4 (&acc)[2][2][4][2], const pg8::Unit& u, int wr, int wc, int fr, int fq, int ui, LAS unsigned char* lds) const {
;         const int row0 = u.pm * 256 + wr * 64 + fr, col0 = u.pn * 128 + wc * 32 + 8 * fq;
; #pragma unroll
;         for (int ai = 0; ai < 2; ++ai)
; #pragma unroll
;             for (int m = 0; m < 4; ++m) {
;                 const float rs = ss ? ((const LAS float*)(lds + 131072))[ui * 256 + wr * 64 + fr + ai * 128 + m * 16] : 1.0f;
;                 float v[8];
; #pragma unroll
;                 for (int n = 0; n < 2; ++n)
; #pragma unroll
;                     for (int j = 0; j < 4; ++j) { const float gt = acc[ai][0][m][n][j] * rs, up = acc[ai][1][m][n][j] * rs; v[n * 4 + j] = gt * up * __builtin_amdgcn_rcpf(1.0f + __builtin_amdgcn_exp2f(-1.4426950408889634f * gt)); }
;                 u32x4 w; w.x = pk2(v[0], v[1]); w.y = pk2(v[2], v[3]); w.z = pk2(v[4], v[5]); w.w = pk2(v[6], v[7]);
;                 *(u32x4*)(H + (size_t)(row0 + ai * 128 + m * 16) * DFF + col0) = w;
.Lxs_p10_j:
	s_barrier
	s_setprio 1
	v_mfma_f32_16x16x32_bf16 v[54:57], v[200:203], v[168:171], v[54:57]
	v_mfma_f32_16x16x32_bf16 v[50:53], v[212:215], v[168:171], v[50:53]
	v_mfma_f32_16x16x32_bf16 v[38:41], v[200:203], v[176:179], v[38:41]
	v_mfma_f32_16x16x32_bf16 v[34:37], v[212:215], v[176:179], v[34:37]
	v_mfma_f32_16x16x32_bf16 v[22:25], v[200:203], v[184:187], v[22:25]
	v_mfma_f32_16x16x32_bf16 v[18:21], v[212:215], v[184:187], v[18:21]
	v_mfma_f32_16x16x32_bf16 v[6:9], v[200:203], v[192:195], v[6:9]
	v_mfma_f32_16x16x32_bf16 v[2:5], v[212:215], v[192:195], v[2:5]
	v_mfma_f32_16x16x32_bf16 v[54:57], v[208:211], v[172:175], v[54:57]
	v_mfma_f32_16x16x32_bf16 v[50:53], v[216:219], v[172:175], v[50:53]
	v_mfma_f32_16x16x32_bf16 v[38:41], v[208:211], v[180:183], v[38:41]
	v_mfma_f32_16x16x32_bf16 v[34:37], v[216:219], v[180:183], v[34:37]
	v_mfma_f32_16x16x32_bf16 v[22:25], v[208:211], v[188:191], v[22:25]
	v_mfma_f32_16x16x32_bf16 v[18:21], v[216:219], v[188:191], v[18:21]
	v_mfma_f32_16x16x32_bf16 v[6:9], v[208:211], v[196:199], v[6:9]
	v_mfma_f32_16x16x32_bf16 v[2:5], v[216:219], v[196:199], v[2:5]
	s_setprio 0
	s_add_i32 s49, s49, 2
	s_add_u32 s18, s18, 0x100
	s_addc_u32 s19, s19, 0
	s_add_u32 s47, s47, 0x100
	s_addc_u32 s48, s48, 0
	s_cmp_gt_u32 s49, 29
	s_barrier
	s_cbranch_scc0 .LBB0_1091
	v_lshl_add_u32 v153, s43, 10, v147
	ds_read2_b32 v[154:155], v153 offset1:16
	v_lshl_or_b32 v156, s44, 7, v148
	v_lshl_add_u32 v152, s16, 8, v1
	v_ashrrev_i32_e32 v157, 31, v156
	s_and_b64 vcc, exec, s[4:5]
	s_waitcnt lgkmcnt(0)
	v_pk_mul_f32 v[126:127], v[126:127], v[154:155] op_sel_hi:[1,0]
	v_pk_mul_f32 v[118:119], v[118:119], v[154:155] op_sel_hi:[1,0]
	v_mul_f32_e32 v158, 0xbfb8aa3b, v126
	v_mul_f32_e32 v159, 0xbfb8aa3b, v127
	v_exp_f32_e32 v158, v158
	v_exp_f32_e32 v159, v159
	v_pk_mul_f32 v[128:129], v[128:129], v[154:155] op_sel_hi:[1,0]
	v_pk_mul_f32 v[118:119], v[126:127], v[118:119]
	v_add_f32_e32 v126, 1.0, v158
	v_add_f32_e32 v127, 1.0, v159
	v_mul_f32_e32 v158, 0xbfb8aa3b, v128
	v_mul_f32_e32 v159, 0xbfb8aa3b, v129
	v_rcp_f32_e32 v126, v126
	v_rcp_f32_e32 v127, v127
	v_exp_f32_e32 v158, v158
	v_exp_f32_e32 v159, v159
	v_pk_mul_f32 v[120:121], v[120:121], v[154:155] op_sel_hi:[1,0]
	v_pk_mul_f32 v[118:119], v[118:119], v[126:127]
	v_add_f32_e32 v126, 1.0, v158
	v_add_f32_e32 v127, 1.0, v159
	v_rcp_f32_e32 v126, v126
	v_rcp_f32_e32 v127, v127
	v_pk_mul_f32 v[122:123], v[122:123], v[154:155] op_sel_hi:[1,0]
	v_pk_mul_f32 v[120:121], v[128:129], v[120:121]
	v_pk_mul_f32 v[114:115], v[114:115], v[154:155] op_sel_hi:[1,0]
	v_mul_f32_e32 v158, 0xbfb8aa3b, v122
	v_pk_mul_f32 v[120:121], v[120:121], v[126:127]
	v_mul_f32_e32 v127, 0xbfb8aa3b, v123
	v_pk_mul_f32 v[114:115], v[122:123], v[114:115]
	v_pk_mul_f32 v[122:123], v[124:125], v[154:155] op_sel_hi:[1,0]
	v_exp_f32_e32 v158, v158
	v_mul_f32_e32 v124, 0xbfb8aa3b, v122
	v_mul_f32_e32 v125, 0xbfb8aa3b, v123
	v_exp_f32_e32 v124, v124
	v_exp_f32_e32 v125, v125
	v_exp_f32_e32 v127, v127
	v_add_f32_e32 v126, 1.0, v158
	v_add_f32_e32 v124, 1.0, v124
	v_add_f32_e32 v125, 1.0, v125
	v_rcp_f32_e32 v124, v124
	v_rcp_f32_e32 v125, v125
	v_add_f32_e32 v127, 1.0, v127
	v_rcp_f32_e32 v126, v126
	v_rcp_f32_e32 v127, v127
	v_pk_mul_f32 v[116:117], v[116:117], v[154:155] op_sel_hi:[1,0]
	s_mov_b32 s44, s8
	v_pk_mul_f32 v[116:117], v[122:123], v[116:117]
	v_pk_mul_f32 v[114:115], v[114:115], v[126:127]
	v_pk_mul_f32 v[122:123], v[116:117], v[124:125]
	v_cvt_pk_bf16_f32 v116, v118, v119
	v_cvt_pk_bf16_f32 v119, v122, v123
	v_mov_b32_e32 v122, v155
	v_pk_mul_f32 v[124:125], v[110:111], v[122:123] op_sel_hi:[1,0]
	v_cvt_pk_bf16_f32 v118, v114, v115
	v_mov_b64_e32 v[114:115], s[0:1]
	v_mul_f32_e32 v110, 0xbfb8aa3b, v124
	v_cvt_pk_bf16_f32 v117, v120, v121
	v_mad_i64_i32 v[120:121], s[18:19], v152, s41, v[114:115]
	v_exp_f32_e32 v123, v110
	v_lshlrev_b64 v[110:111], 1, v[156:157]
	v_lshl_add_u64 v[120:121], v[120:121], 0, v[110:111]
	global_store_dwordx4 v[120:121], v[116:119], off
	v_pk_mul_f32 v[112:113], v[112:113], v[122:123] op_sel_hi:[1,0]
	v_pk_mul_f32 v[102:103], v[102:103], v[122:123] op_sel_hi:[1,0]
	v_mul_f32_e32 v117, 0xbfb8aa3b, v125
	v_exp_f32_e32 v117, v117
	v_add_f32_e32 v116, 1.0, v123
	v_mul_f32_e32 v118, 0xbfb8aa3b, v112
	v_rcp_f32_e32 v116, v116
	v_add_f32_e32 v117, 1.0, v117
	v_rcp_f32_e32 v117, v117
	v_exp_f32_e32 v118, v118
	v_pk_mul_f32 v[102:103], v[124:125], v[102:103]
	v_pk_mul_f32 v[106:107], v[106:107], v[122:123] op_sel_hi:[1,0]
	v_pk_mul_f32 v[104:105], v[104:105], v[122:123] op_sel_hi:[1,0]
	v_mul_f32_e32 v119, 0xbfb8aa3b, v113
	v_pk_mul_f32 v[102:103], v[102:103], v[116:117]
	v_add_f32_e32 v116, 1.0, v118
	v_mul_f32_e32 v118, 0xbfb8aa3b, v106
	v_pk_mul_f32 v[104:105], v[112:113], v[104:105]
	v_mul_f32_e32 v113, 0xbfb8aa3b, v107
	v_pk_mul_f32 v[98:99], v[98:99], v[122:123] op_sel_hi:[1,0]
	v_exp_f32_e32 v118, v118
	v_exp_f32_e32 v113, v113
	v_pk_mul_f32 v[98:99], v[106:107], v[98:99]
	v_pk_mul_f32 v[106:107], v[108:109], v[122:123] op_sel_hi:[1,0]
	v_add_f32_e32 v112, 1.0, v118
	v_mul_f32_e32 v108, 0xbfb8aa3b, v106
	v_mul_f32_e32 v109, 0xbfb8aa3b, v107
	v_exp_f32_e32 v108, v108
	v_exp_f32_e32 v109, v109
	v_add_f32_e32 v113, 1.0, v113
	v_rcp_f32_e32 v112, v112
	v_rcp_f32_e32 v113, v113
	v_add_f32_e32 v108, 1.0, v108
	v_add_f32_e32 v109, 1.0, v109
	v_exp_f32_e32 v119, v119
	v_rcp_f32_e32 v108, v108
	v_rcp_f32_e32 v109, v109
	v_pk_mul_f32 v[112:113], v[98:99], v[112:113]
	v_pk_mul_f32 v[98:99], v[100:101], v[122:123] op_sel_hi:[1,0]
	v_add_f32_e32 v117, 1.0, v119
	v_pk_mul_f32 v[98:99], v[106:107], v[98:99]
	v_rcp_f32_e32 v116, v116
	v_pk_mul_f32 v[106:107], v[98:99], v[108:109]
	v_cvt_pk_bf16_f32 v98, v102, v103
	ds_read2_b32 v[102:103], v153 offset0:32 offset1:48
	v_rcp_f32_e32 v117, v117
	v_cvt_pk_bf16_f32 v101, v106, v107
	v_cvt_pk_bf16_f32 v100, v112, v113
	s_mov_b32 s16, s10
	v_pk_mul_f32 v[104:105], v[104:105], v[116:117]
	s_waitcnt lgkmcnt(0)
; #define LAS __attribute__((address_space(3)))
; DI unsigned pk2(float a, float b) { f32x2_t v = {a, b}; return __builtin_bit_cast(unsigned, __builtin_convertvector(v, bf16x2_t)); }
;     DI void operator()(const f32x4 (&acc)[2][2][4][2], const pg8::Unit& u, int wr, int wc, int fr, int fq, int ui, LAS unsigned char* lds) const {
;         const int row0 = u.pm * 256 + wr * 64 + fr, col0 = u.pn * 128 + wc * 32 + 8 * fq;
; #pragma unroll
;         for (int ai = 0; ai < 2; ++ai)
; #pragma unroll
;             for (int m = 0; m < 4; ++m) {
;                 const float rs = ss ? ((const LAS float*)(lds + 131072))[ui * 256 + wr * 64 + fr + ai * 128 + m * 16] : 1.0f;
;                 float v[8];
; #pragma unroll
;                 for (int n = 0; n < 2; ++n)
; #pragma unroll
;                     for (int j = 0; j < 4; ++j) { const float gt = acc[ai][0][m][n][j] * rs, up = acc[ai][1][m][n][j] * rs; v[n * 4 + j] = gt * up * __builtin_amdgcn_rcpf(1.0f + __builtin_amdgcn_exp2f(-1.4426950408889634f * gt)); }
;                 u32x4 w; w.x = pk2(v[0], v[1]); w.y = pk2(v[2], v[3]); w.z = pk2(v[4], v[5]); w.w = pk2(v[6], v[7]);
;                 *(u32x4*)(H + (size_t)(row0 + ai * 128 + m * 16) * DFF + col0) = w;
	v_pk_mul_f32 v[94:95], v[94:95], v[102:103] op_sel_hi:[1,0]
	v_cvt_pk_bf16_f32 v99, v104, v105
	v_or_b32_e32 v104, 16, v152
	v_mul_f32_e32 v105, 0xbfb8aa3b, v94
	v_exp_f32_e32 v106, v105
	v_mad_i64_i32 v[104:105], s[18:19], v104, s41, v[114:115]
	v_lshl_add_u64 v[104:105], v[104:105], 0, v[110:111]
	global_store_dwordx4 v[104:105], v[98:101], off
	v_pk_mul_f32 v[86:87], v[86:87], v[102:103] op_sel_hi:[1,0]
	v_pk_mul_f32 v[90:91], v[90:91], v[102:103] op_sel_hi:[1,0]
	v_mul_f32_e32 v99, 0xbfb8aa3b, v95
	v_exp_f32_e32 v99, v99
	v_add_f32_e32 v98, 1.0, v106
	v_pk_mul_f32 v[86:87], v[94:95], v[86:87]
	v_rcp_f32_e32 v98, v98
	v_add_f32_e32 v94, 1.0, v99
	v_rcp_f32_e32 v99, v94
	v_pk_mul_f32 v[94:95], v[96:97], v[102:103] op_sel_hi:[1,0]
	v_pk_mul_f32 v[88:89], v[88:89], v[102:103] op_sel_hi:[1,0]
	v_mul_f32_e32 v97, 0xbfb8aa3b, v95
	v_pk_mul_f32 v[86:87], v[86:87], v[98:99]
	v_mul_f32_e32 v98, 0xbfb8aa3b, v90
	v_pk_mul_f32 v[88:89], v[94:95], v[88:89]
	v_mul_f32_e32 v95, 0xbfb8aa3b, v91
	v_pk_mul_f32 v[82:83], v[82:83], v[102:103] op_sel_hi:[1,0]
	v_exp_f32_e32 v98, v98
	v_exp_f32_e32 v95, v95
	v_pk_mul_f32 v[82:83], v[90:91], v[82:83]
	v_pk_mul_f32 v[90:91], v[92:93], v[102:103] op_sel_hi:[1,0]
	v_mul_f32_e32 v96, 0xbfb8aa3b, v94
	v_mul_f32_e32 v92, 0xbfb8aa3b, v90
	v_mul_f32_e32 v93, 0xbfb8aa3b, v91
	v_exp_f32_e32 v92, v92
	v_exp_f32_e32 v93, v93
	v_exp_f32_e32 v96, v96
	v_exp_f32_e32 v97, v97
	v_add_f32_e32 v94, 1.0, v98
	v_add_f32_e32 v95, 1.0, v95
	v_rcp_f32_e32 v94, v94
	v_rcp_f32_e32 v95, v95
	v_add_f32_e32 v92, 1.0, v92
	v_add_f32_e32 v93, 1.0, v93
	v_add_f32_e32 v96, 1.0, v96
	v_add_f32_e32 v97, 1.0, v97
	v_rcp_f32_e32 v92, v92
	v_rcp_f32_e32 v93, v93
	v_rcp_f32_e32 v96, v96
	v_rcp_f32_e32 v97, v97
	v_pk_mul_f32 v[94:95], v[82:83], v[94:95]
	v_pk_mul_f32 v[82:83], v[84:85], v[102:103] op_sel_hi:[1,0]
	v_cvt_pk_bf16_f32 v84, v94, v95
	v_pk_mul_f32 v[82:83], v[90:91], v[82:83]
	v_pk_mul_f32 v[88:89], v[88:89], v[96:97]
	v_pk_mul_f32 v[90:91], v[82:83], v[92:93]
	v_cvt_pk_bf16_f32 v82, v86, v87
	v_or_b32_e32 v87, 32, v152
	v_mov_b32_e32 v86, v103
	v_pk_mul_f32 v[78:79], v[78:79], v[86:87] op_sel_hi:[1,0]
	v_cvt_pk_bf16_f32 v83, v88, v89
	v_mul_f32_e32 v88, 0xbfb8aa3b, v78
	v_cvt_pk_bf16_f32 v85, v90, v91
	v_exp_f32_e32 v90, v88
	v_mad_i64_i32 v[88:89], s[18:19], v87, s41, v[114:115]
	v_lshl_add_u64 v[88:89], v[88:89], 0, v[110:111]
	global_store_dwordx4 v[88:89], v[82:85], off
	v_pk_mul_f32 v[70:71], v[70:71], v[86:87] op_sel_hi:[1,0]
	v_pk_mul_f32 v[74:75], v[74:75], v[86:87] op_sel_hi:[1,0]
	v_mul_f32_e32 v83, 0xbfb8aa3b, v79
	v_exp_f32_e32 v83, v83
	v_add_f32_e32 v82, 1.0, v90
	v_pk_mul_f32 v[70:71], v[78:79], v[70:71]
	v_rcp_f32_e32 v82, v82
	v_add_f32_e32 v78, 1.0, v83
	v_rcp_f32_e32 v83, v78
	v_pk_mul_f32 v[78:79], v[80:81], v[86:87] op_sel_hi:[1,0]
	v_pk_mul_f32 v[72:73], v[72:73], v[86:87] op_sel_hi:[1,0]
	v_mul_f32_e32 v81, 0xbfb8aa3b, v79
	v_pk_mul_f32 v[70:71], v[70:71], v[82:83]
	v_mul_f32_e32 v82, 0xbfb8aa3b, v74
	v_pk_mul_f32 v[72:73], v[78:79], v[72:73]
	v_mul_f32_e32 v79, 0xbfb8aa3b, v75
	v_pk_mul_f32 v[66:67], v[66:67], v[86:87] op_sel_hi:[1,0]
	v_exp_f32_e32 v82, v82
	v_exp_f32_e32 v79, v79
	v_pk_mul_f32 v[66:67], v[74:75], v[66:67]
	v_pk_mul_f32 v[74:75], v[76:77], v[86:87] op_sel_hi:[1,0]
	v_mul_f32_e32 v80, 0xbfb8aa3b, v78
	v_mul_f32_e32 v76, 0xbfb8aa3b, v74
	v_mul_f32_e32 v77, 0xbfb8aa3b, v75
	v_exp_f32_e32 v76, v76
	v_exp_f32_e32 v77, v77
	v_exp_f32_e32 v80, v80
	v_exp_f32_e32 v81, v81
	v_add_f32_e32 v78, 1.0, v82
	v_add_f32_e32 v79, 1.0, v79
	v_rcp_f32_e32 v78, v78
	v_rcp_f32_e32 v79, v79
	v_add_f32_e32 v76, 1.0, v76
	v_add_f32_e32 v77, 1.0, v77
	v_rcp_f32_e32 v76, v76
	v_rcp_f32_e32 v77, v77
	v_add_f32_e32 v80, 1.0, v80
	v_add_f32_e32 v81, 1.0, v81
	v_rcp_f32_e32 v80, v80
	v_rcp_f32_e32 v81, v81
	v_pk_mul_f32 v[78:79], v[66:67], v[78:79]
	v_pk_mul_f32 v[66:67], v[68:69], v[86:87] op_sel_hi:[1,0]
	v_cvt_pk_bf16_f32 v68, v78, v79
	v_pk_mul_f32 v[66:67], v[74:75], v[66:67]
	v_pk_mul_f32 v[72:73], v[72:73], v[80:81]
	v_pk_mul_f32 v[74:75], v[66:67], v[76:77]
	v_cvt_pk_bf16_f32 v66, v70, v71
	ds_read2_b32 v[70:71], v153 offset0:128 offset1:144
	v_cvt_pk_bf16_f32 v67, v72, v73
	v_or_b32_e32 v72, 48, v152
	v_mad_i64_i32 v[72:73], s[18:19], v72, s41, v[114:115]
	v_cvt_pk_bf16_f32 v69, v74, v75
	s_waitcnt lgkmcnt(0)
; #define LAS __attribute__((address_space(3)))
; DI unsigned pk2(float a, float b) { f32x2_t v = {a, b}; return __builtin_bit_cast(unsigned, __builtin_convertvector(v, bf16x2_t)); }
;     DI void operator()(const f32x4 (&acc)[2][2][4][2], const pg8::Unit& u, int wr, int wc, int fr, int fq, int ui, LAS unsigned char* lds) const {
;         const int row0 = u.pm * 256 + wr * 64 + fr, col0 = u.pn * 128 + wc * 32 + 8 * fq;
; #pragma unroll
;         for (int ai = 0; ai < 2; ++ai)
; #pragma unroll
;             for (int m = 0; m < 4; ++m) {
;                 const float rs = ss ? ((const LAS float*)(lds + 131072))[ui * 256 + wr * 64 + fr + ai * 128 + m * 16] : 1.0f;
;                 float v[8];
; #pragma unroll
;                 for (int n = 0; n < 2; ++n)
; #pragma unroll
;                     for (int j = 0; j < 4; ++j) { const float gt = acc[ai][0][m][n][j] * rs, up = acc[ai][1][m][n][j] * rs; v[n * 4 + j] = gt * up * __builtin_amdgcn_rcpf(1.0f + __builtin_amdgcn_exp2f(-1.4426950408889634f * gt)); }
;                 u32x4 w; w.x = pk2(v[0], v[1]); w.y = pk2(v[2], v[3]); w.z = pk2(v[4], v[5]); w.w = pk2(v[6], v[7]);
;                 *(u32x4*)(H + (size_t)(row0 + ai * 128 + m * 16) * DFF + col0) = w;
	v_pk_mul_f32 v[62:63], v[62:63], v[70:71] op_sel_hi:[1,0]
	v_lshl_add_u64 v[72:73], v[72:73], 0, v[110:111]
	v_mul_f32_e32 v74, 0xbfb8aa3b, v62
	global_store_dwordx4 v[72:73], v[66:69], off
	v_exp_f32_e32 v74, v74
	v_pk_mul_f32 v[54:55], v[54:55], v[70:71] op_sel_hi:[1,0]
	v_mul_f32_e32 v67, 0xbfb8aa3b, v63
	v_exp_f32_e32 v67, v67
	v_add_f32_e32 v66, 1.0, v74
	v_pk_mul_f32 v[54:55], v[62:63], v[54:55]
	v_rcp_f32_e32 v66, v66
	v_add_f32_e32 v62, 1.0, v67
	v_rcp_f32_e32 v67, v62
	v_pk_mul_f32 v[62:63], v[64:65], v[70:71] op_sel_hi:[1,0]
	v_pk_mul_f32 v[58:59], v[58:59], v[70:71] op_sel_hi:[1,0]
	v_pk_mul_f32 v[56:57], v[56:57], v[70:71] op_sel_hi:[1,0]
	v_mul_f32_e32 v65, 0xbfb8aa3b, v63
	v_pk_mul_f32 v[54:55], v[54:55], v[66:67]
	v_mul_f32_e32 v66, 0xbfb8aa3b, v58
	v_pk_mul_f32 v[56:57], v[62:63], v[56:57]
	v_mul_f32_e32 v63, 0xbfb8aa3b, v59
	v_pk_mul_f32 v[50:51], v[50:51], v[70:71] op_sel_hi:[1,0]
	v_exp_f32_e32 v66, v66
	v_exp_f32_e32 v63, v63
	v_pk_mul_f32 v[50:51], v[58:59], v[50:51]
	v_pk_mul_f32 v[58:59], v[60:61], v[70:71] op_sel_hi:[1,0]
	v_mul_f32_e32 v64, 0xbfb8aa3b, v62
	v_mul_f32_e32 v60, 0xbfb8aa3b, v58
	v_mul_f32_e32 v61, 0xbfb8aa3b, v59
	v_exp_f32_e32 v64, v64
	v_exp_f32_e32 v65, v65
	v_exp_f32_e32 v60, v60
	v_exp_f32_e32 v61, v61
	v_add_f32_e32 v62, 1.0, v66
	v_add_f32_e32 v63, 1.0, v63
	v_rcp_f32_e32 v62, v62
	v_rcp_f32_e32 v63, v63
	v_add_f32_e32 v64, 1.0, v64
	v_add_f32_e32 v65, 1.0, v65
	v_add_f32_e32 v60, 1.0, v60
	v_add_f32_e32 v61, 1.0, v61
	v_rcp_f32_e32 v64, v64
	v_rcp_f32_e32 v65, v65
	v_rcp_f32_e32 v60, v60
	v_rcp_f32_e32 v61, v61
	v_pk_mul_f32 v[62:63], v[50:51], v[62:63]
	v_pk_mul_f32 v[50:51], v[52:53], v[70:71] op_sel_hi:[1,0]
	v_add_u32_e32 v68, 0x80, v152
	v_pk_mul_f32 v[50:51], v[58:59], v[50:51]
	v_pk_mul_f32 v[56:57], v[56:57], v[64:65]
	v_pk_mul_f32 v[58:59], v[50:51], v[60:61]
	v_cvt_pk_bf16_f32 v50, v54, v55
	v_mov_b32_e32 v54, v71
	v_cvt_pk_bf16_f32 v51, v56, v57
	v_pk_mul_f32 v[46:47], v[46:47], v[54:55] op_sel_hi:[1,0]
	v_mad_i64_i32 v[56:57], s[18:19], v68, s41, v[114:115]
	v_cvt_pk_bf16_f32 v52, v62, v63
	v_cvt_pk_bf16_f32 v53, v58, v59
	v_mul_f32_e32 v55, 0xbfb8aa3b, v46
	v_lshl_add_u64 v[56:57], v[56:57], 0, v[110:111]
	v_exp_f32_e32 v55, v55
	global_store_dwordx4 v[56:57], v[50:53], off
	s_mov_b64 s[20:21], s[14:15]
	s_mov_b32 s43, s42
	v_mul_f32_e32 v51, 0xbfb8aa3b, v47
	v_exp_f32_e32 v51, v51
	v_pk_mul_f32 v[38:39], v[38:39], v[54:55] op_sel_hi:[1,0]
	v_add_f32_e32 v50, 1.0, v55
	v_pk_mul_f32 v[38:39], v[46:47], v[38:39]
	v_add_f32_e32 v46, 1.0, v51
	v_rcp_f32_e32 v50, v50
	v_rcp_f32_e32 v51, v46
	v_pk_mul_f32 v[46:47], v[48:49], v[54:55] op_sel_hi:[1,0]
	v_pk_mul_f32 v[42:43], v[42:43], v[54:55] op_sel_hi:[1,0]
	v_pk_mul_f32 v[40:41], v[40:41], v[54:55] op_sel_hi:[1,0]
	v_mul_f32_e32 v49, 0xbfb8aa3b, v47
	v_pk_mul_f32 v[38:39], v[38:39], v[50:51]
	v_mul_f32_e32 v50, 0xbfb8aa3b, v42
	v_pk_mul_f32 v[40:41], v[46:47], v[40:41]
	v_mul_f32_e32 v47, 0xbfb8aa3b, v43
	v_pk_mul_f32 v[34:35], v[34:35], v[54:55] op_sel_hi:[1,0]
	v_exp_f32_e32 v50, v50
	v_exp_f32_e32 v47, v47
	v_pk_mul_f32 v[34:35], v[42:43], v[34:35]
	v_pk_mul_f32 v[42:43], v[44:45], v[54:55] op_sel_hi:[1,0]
	v_mul_f32_e32 v48, 0xbfb8aa3b, v46
	v_mul_f32_e32 v44, 0xbfb8aa3b, v42
	v_mul_f32_e32 v45, 0xbfb8aa3b, v43
	v_exp_f32_e32 v44, v44
	v_exp_f32_e32 v45, v45
	v_add_f32_e32 v46, 1.0, v50
	v_add_f32_e32 v47, 1.0, v47
	v_rcp_f32_e32 v46, v46
	v_rcp_f32_e32 v47, v47
	v_add_f32_e32 v44, 1.0, v44
	v_add_f32_e32 v45, 1.0, v45
	v_exp_f32_e32 v48, v48
	v_exp_f32_e32 v49, v49
	v_rcp_f32_e32 v44, v44
	v_rcp_f32_e32 v45, v45
	v_pk_mul_f32 v[46:47], v[34:35], v[46:47]
	v_pk_mul_f32 v[34:35], v[36:37], v[54:55] op_sel_hi:[1,0]
	v_add_f32_e32 v48, 1.0, v48
	v_pk_mul_f32 v[34:35], v[42:43], v[34:35]
	v_add_f32_e32 v49, 1.0, v49
	v_pk_mul_f32 v[42:43], v[34:35], v[44:45]
	v_cvt_pk_bf16_f32 v34, v38, v39
	ds_read2_b32 v[38:39], v153 offset0:160 offset1:176
	v_rcp_f32_e32 v48, v48
	v_rcp_f32_e32 v49, v49
	v_cvt_pk_bf16_f32 v37, v42, v43
	v_cvt_pk_bf16_f32 v36, v46, v47
	s_waitcnt lgkmcnt(0)
; #define LAS __attribute__((address_space(3)))
; DI unsigned pk2(float a, float b) { f32x2_t v = {a, b}; return __builtin_bit_cast(unsigned, __builtin_convertvector(v, bf16x2_t)); }
; #define PG8_WAIT_V(n) asm volatile("s_waitcnt vmcnt(" #n ")" ::: "memory")
; #define PG8_BAR __builtin_amdgcn_s_barrier()
; template <class Epi, class Sched>
; __device__ __forceinline__ void gemm_phase(LAS unsigned char* lds, const Gemm g, const Sched& S, const Epi& E) {
;     ...
;     PG8_WAIT_V(0);
;     if (wr == 0) PG8_BAR;
;     PG8_BAR;
;     DI void operator()(const f32x4 (&acc)[2][2][4][2], const pg8::Unit& u, int wr, int wc, int fr, int fq, int ui, LAS unsigned char* lds) const {
;     ...
;                 const float rs = ss ? ((const LAS float*)(lds + 131072))[ui * 256 + wr * 64 + fr + ai * 128 + m * 16] : 1.0f;
;                 float v[8];
; #pragma unroll
;                 for (int n = 0; n < 2; ++n)
; #pragma unroll
;                     for (int j = 0; j < 4; ++j) { const float gt = acc[ai][0][m][n][j] * rs, up = acc[ai][1][m][n][j] * rs; v[n * 4 + j] = gt * up * __builtin_amdgcn_rcpf(1.0f + __builtin_amdgcn_exp2f(-1.4426950408889634f * gt)); }
;                 u32x4 w; w.x = pk2(v[0], v[1]); w.y = pk2(v[2], v[3]); w.z = pk2(v[4], v[5]); w.w = pk2(v[6], v[7]);
;                 *(u32x4*)(H + (size_t)(row0 + ai * 128 + m * 16) * DFF + col0) = w;
	v_pk_mul_f32 v[30:31], v[30:31], v[38:39] op_sel_hi:[1,0]
	v_pk_mul_f32 v[40:41], v[40:41], v[48:49]
	v_pk_mul_f32 v[22:23], v[22:23], v[38:39] op_sel_hi:[1,0]
	v_cvt_pk_bf16_f32 v35, v40, v41
	v_add_u32_e32 v40, 0x90, v152
	v_mul_f32_e32 v41, 0xbfb8aa3b, v30
	v_exp_f32_e32 v42, v41
	v_mad_i64_i32 v[40:41], s[18:19], v40, s41, v[114:115]
	v_lshl_add_u64 v[40:41], v[40:41], 0, v[110:111]
	global_store_dwordx4 v[40:41], v[34:37], off
	v_pk_mul_f32 v[22:23], v[30:31], v[22:23]
	v_pk_mul_f32 v[26:27], v[26:27], v[38:39] op_sel_hi:[1,0]
	v_mul_f32_e32 v35, 0xbfb8aa3b, v31
	v_exp_f32_e32 v35, v35
	v_add_f32_e32 v34, 1.0, v42
	v_rcp_f32_e32 v34, v34
	v_pk_mul_f32 v[24:25], v[24:25], v[38:39] op_sel_hi:[1,0]
	v_add_f32_e32 v30, 1.0, v35
	v_rcp_f32_e32 v35, v30
	v_pk_mul_f32 v[30:31], v[32:33], v[38:39] op_sel_hi:[1,0]
	v_pk_mul_f32 v[18:19], v[18:19], v[38:39] op_sel_hi:[1,0]
	v_mul_f32_e32 v33, 0xbfb8aa3b, v31
	v_pk_mul_f32 v[22:23], v[22:23], v[34:35]
	v_mul_f32_e32 v34, 0xbfb8aa3b, v26
	v_pk_mul_f32 v[24:25], v[30:31], v[24:25]
	v_mul_f32_e32 v31, 0xbfb8aa3b, v27
	v_exp_f32_e32 v34, v34
	v_exp_f32_e32 v31, v31
	v_pk_mul_f32 v[18:19], v[26:27], v[18:19]
	v_pk_mul_f32 v[26:27], v[28:29], v[38:39] op_sel_hi:[1,0]
	v_mul_f32_e32 v32, 0xbfb8aa3b, v30
	v_mul_f32_e32 v28, 0xbfb8aa3b, v26
	v_mul_f32_e32 v29, 0xbfb8aa3b, v27
	v_exp_f32_e32 v28, v28
	v_exp_f32_e32 v29, v29
	v_exp_f32_e32 v32, v32
	v_exp_f32_e32 v33, v33
	v_add_f32_e32 v30, 1.0, v34
	v_add_f32_e32 v31, 1.0, v31
	v_rcp_f32_e32 v30, v30
	v_rcp_f32_e32 v31, v31
	v_add_f32_e32 v28, 1.0, v28
	v_add_f32_e32 v29, 1.0, v29
	v_add_f32_e32 v32, 1.0, v32
	v_add_f32_e32 v33, 1.0, v33
	v_rcp_f32_e32 v28, v28
	v_rcp_f32_e32 v29, v29
	v_rcp_f32_e32 v32, v32
	v_rcp_f32_e32 v33, v33
	v_pk_mul_f32 v[30:31], v[18:19], v[30:31]
	v_pk_mul_f32 v[18:19], v[20:21], v[38:39] op_sel_hi:[1,0]
	v_cvt_pk_bf16_f32 v20, v30, v31
	v_pk_mul_f32 v[18:19], v[26:27], v[18:19]
	v_pk_mul_f32 v[24:25], v[24:25], v[32:33]
	v_pk_mul_f32 v[26:27], v[18:19], v[28:29]
	v_cvt_pk_bf16_f32 v18, v22, v23
	v_add_u32_e32 v23, 0xa0, v152
	v_mov_b32_e32 v22, v39
	v_pk_mul_f32 v[14:15], v[14:15], v[22:23] op_sel_hi:[1,0]
	v_cvt_pk_bf16_f32 v19, v24, v25
	v_mul_f32_e32 v24, 0xbfb8aa3b, v14
	v_cvt_pk_bf16_f32 v21, v26, v27
	v_exp_f32_e32 v26, v24
	v_mad_i64_i32 v[24:25], s[18:19], v23, s41, v[114:115]
	v_lshl_add_u64 v[24:25], v[24:25], 0, v[110:111]
	global_store_dwordx4 v[24:25], v[18:21], off
	v_pk_mul_f32 v[6:7], v[6:7], v[22:23] op_sel_hi:[1,0]
	v_pk_mul_f32 v[10:11], v[10:11], v[22:23] op_sel_hi:[1,0]
	v_mul_f32_e32 v19, 0xbfb8aa3b, v15
	v_exp_f32_e32 v19, v19
	v_add_f32_e32 v18, 1.0, v26
	v_pk_mul_f32 v[6:7], v[14:15], v[6:7]
	v_rcp_f32_e32 v18, v18
	v_add_f32_e32 v14, 1.0, v19
	v_rcp_f32_e32 v19, v14
	v_pk_mul_f32 v[14:15], v[16:17], v[22:23] op_sel_hi:[1,0]
	v_pk_mul_f32 v[8:9], v[8:9], v[22:23] op_sel_hi:[1,0]
	v_mul_f32_e32 v17, 0xbfb8aa3b, v15
	v_pk_mul_f32 v[6:7], v[6:7], v[18:19]
	v_mul_f32_e32 v18, 0xbfb8aa3b, v10
	v_pk_mul_f32 v[8:9], v[14:15], v[8:9]
	v_mul_f32_e32 v15, 0xbfb8aa3b, v11
	v_pk_mul_f32 v[2:3], v[2:3], v[22:23] op_sel_hi:[1,0]
	v_exp_f32_e32 v18, v18
	v_exp_f32_e32 v15, v15
	v_pk_mul_f32 v[2:3], v[10:11], v[2:3]
	v_pk_mul_f32 v[10:11], v[12:13], v[22:23] op_sel_hi:[1,0]
	v_mul_f32_e32 v16, 0xbfb8aa3b, v14
	v_mul_f32_e32 v12, 0xbfb8aa3b, v10
	v_mul_f32_e32 v13, 0xbfb8aa3b, v11
	v_exp_f32_e32 v12, v12
	v_exp_f32_e32 v13, v13
	v_exp_f32_e32 v16, v16
	v_exp_f32_e32 v17, v17
	v_add_f32_e32 v14, 1.0, v18
	v_add_f32_e32 v15, 1.0, v15
	v_rcp_f32_e32 v14, v14
	v_rcp_f32_e32 v15, v15
	v_add_f32_e32 v12, 1.0, v12
	v_add_f32_e32 v13, 1.0, v13
	v_add_f32_e32 v16, 1.0, v16
	v_add_f32_e32 v17, 1.0, v17
	v_rcp_f32_e32 v12, v12
	v_rcp_f32_e32 v13, v13
	v_rcp_f32_e32 v16, v16
	v_rcp_f32_e32 v17, v17
	v_pk_mul_f32 v[14:15], v[2:3], v[14:15]
	v_pk_mul_f32 v[2:3], v[4:5], v[22:23] op_sel_hi:[1,0]
	v_cvt_pk_bf16_f32 v4, v14, v15
	v_pk_mul_f32 v[2:3], v[10:11], v[2:3]
	v_pk_mul_f32 v[8:9], v[8:9], v[16:17]
	v_pk_mul_f32 v[10:11], v[2:3], v[12:13]
	v_cvt_pk_bf16_f32 v2, v6, v7
	v_add_u32_e32 v6, 0xb0, v152
	v_mad_i64_i32 v[6:7], s[18:19], v6, s41, v[114:115]
	v_cvt_pk_bf16_f32 v3, v8, v9
	v_cvt_pk_bf16_f32 v5, v10, v11
	v_lshl_add_u64 v[6:7], v[6:7], 0, v[110:111]
	s_mov_b64 s[18:19], s[12:13]
	global_store_dwordx4 v[6:7], v[2:5], off
	s_cbranch_vccz .LBB0_1088
	s_waitcnt vmcnt(0)
	s_cmpk_gt_u32 s26, 0xff
	s_cbranch_scc1 .LBB0_1095
	s_barrier
